# GU epilogue: ssq row loads issued together; rstd via plain v_rsq (x>=eps never denormal) instead of hipcc's denormal rescue sequence
# speedup vs baseline: 1.0071x; 1.0071x over previous
; #define MFMA16(a, b, c) __builtin_amdgcn_mfma_f32_16x16x32_bf16((a), (b), (c), 0, 0, 0)
; template <class Epi>
; DI void gemm8_tile(const bf16_t* __restrict__ Ab, int lda, const bf16_t* __restrict__ Bb, int ldb, int K, int brow, int bcol, const Epi epi,
;                    bool staged, bool has_next, const bf16_t* __restrict__ Abn, const bf16_t* __restrict__ Bbn) {
;     ...
;       for (int m = 0; m < 8; ++m)
; #pragma unroll
;         for (int n = 0; n < 4; ++n) acc[m][n] = MFMA16(At[m], Bf[n], acc[m][n]);
;       __builtin_amdgcn_sched_barrier(0);
;     }
;     asm volatile("s_waitcnt vmcnt(0)" ::: "memory");
;     __syncthreads();
;   DI void run8(f32x4 (&acc)[8][4], int rb, int cb, int fr, int fq) const {
;     const int lane = fq * 16 + fr, wid = (int)(threadIdx.x >> 6);
;     bf16_t* scr = (bf16_t*)(smem + G8_STAGE_B + wid * 1280);
;     const int srow = lane >> 2, sch = lane & 3;
;     bf16_t* ap = act + (size_t)(rb + srow) * LDA + (cb >> 1) + sch * 8;
;     float rsv[8][4];
; #pragma unroll
;     for (int m = 0; m < 8; ++m)
; #pragma unroll
;       for (int j = 0; j < 4; ++j) rsv[m][j] = rsqrtf(ssq[rb + m * 16 + fq * 4 + j] * (1.f / D) + EPS);
.LBB0_456:
	s_waitcnt lgkmcnt(0)
	v_mfma_f32_16x16x32_bf16 v[122:125], v[58:61], v[2:5], v[126:129]
	v_mfma_f32_16x16x32_bf16 v[126:129], v[58:61], v[138:141], v[146:149]
	v_mfma_f32_16x16x32_bf16 v[114:117], v[58:61], v[142:145], v[118:121]
	v_mfma_f32_16x16x32_bf16 v[118:121], v[58:61], v[202:205], v[150:153]
	v_mfma_f32_16x16x32_bf16 v[106:109], v[50:53], v[2:5], v[110:113]
	v_mfma_f32_16x16x32_bf16 v[110:113], v[50:53], v[138:141], v[154:157]
	v_mfma_f32_16x16x32_bf16 v[98:101], v[50:53], v[142:145], v[102:105]
	v_mfma_f32_16x16x32_bf16 v[102:105], v[50:53], v[202:205], v[158:161]
	v_mfma_f32_16x16x32_bf16 v[90:93], v[42:45], v[2:5], v[94:97]
	v_mfma_f32_16x16x32_bf16 v[94:97], v[42:45], v[138:141], v[162:165]
	v_mfma_f32_16x16x32_bf16 v[82:85], v[42:45], v[142:145], v[86:89]
	v_mfma_f32_16x16x32_bf16 v[86:89], v[42:45], v[202:205], v[166:169]
	v_mfma_f32_16x16x32_bf16 v[74:77], v[34:37], v[2:5], v[78:81]
	v_mfma_f32_16x16x32_bf16 v[78:81], v[34:37], v[138:141], v[170:173]
	v_mfma_f32_16x16x32_bf16 v[66:69], v[34:37], v[142:145], v[70:73]
	v_mfma_f32_16x16x32_bf16 v[70:73], v[34:37], v[202:205], v[174:177]
	v_mfma_f32_16x16x32_bf16 v[58:61], v[26:29], v[2:5], v[62:65]
	v_mfma_f32_16x16x32_bf16 v[62:65], v[26:29], v[138:141], v[178:181]
	v_mfma_f32_16x16x32_bf16 v[50:53], v[26:29], v[142:145], v[54:57]
	v_mfma_f32_16x16x32_bf16 v[54:57], v[26:29], v[202:205], v[182:185]
	v_mfma_f32_16x16x32_bf16 v[42:45], v[18:21], v[2:5], v[46:49]
	v_mfma_f32_16x16x32_bf16 v[46:49], v[18:21], v[138:141], v[186:189]
	v_mfma_f32_16x16x32_bf16 v[34:37], v[18:21], v[142:145], v[38:41]
	v_mfma_f32_16x16x32_bf16 v[38:41], v[18:21], v[202:205], v[190:193]
	v_mfma_f32_16x16x32_bf16 v[26:29], v[10:13], v[2:5], v[30:33]
	v_mfma_f32_16x16x32_bf16 v[30:33], v[10:13], v[138:141], v[194:197]
	v_mfma_f32_16x16x32_bf16 v[18:21], v[10:13], v[142:145], v[22:25]
	v_mfma_f32_16x16x32_bf16 v[22:25], v[10:13], v[202:205], v[198:201]
	v_mfma_f32_16x16x32_bf16 v[10:13], v[206:209], v[2:5], v[14:17]
	v_mfma_f32_16x16x32_bf16 v[14:17], v[206:209], v[138:141], v[130:133]
	v_mfma_f32_16x16x32_bf16 v[2:5], v[206:209], v[142:145], v[6:9]
	v_mfma_f32_16x16x32_bf16 v[6:9], v[206:209], v[202:205], v[134:137]
	v_lshrrev_b32_e32 v168, 4, v228
	v_add_u32_e32 v130, s3, v230
	v_lshl_or_b32 v131, v229, 6, s31
	v_or_b32_e32 v0, v130, v222
	v_lshl_or_b32 v130, v168, 2, v130
	v_ashrrev_i32_e32 v134, 1, v131
	v_ashrrev_i32_e32 v131, 31, v130
	v_lshl_add_u64 v[130:131], v[130:131], 2, s[4:5]
	s_waitcnt vmcnt(0)
	s_waitcnt vmcnt(0)
	s_barrier
	global_load_dwordx4 v[138:141], v[130:131], off
	global_load_dwordx4 v[176:179], v[130:131], off offset:64
	global_load_dwordx4 v[180:183], v[130:131], off offset:128
	global_load_dwordx4 v[184:187], v[130:131], off offset:192
	global_load_dwordx4 v[188:191], v[130:131], off offset:256
	global_load_dwordx4 v[192:195], v[130:131], off offset:320
	global_load_dwordx4 v[170:173], v[130:131], off offset:384
	global_load_dwordx4 v[196:199], v[130:131], off offset:448
	s_mov_b32 s0, 0x358637bd
	v_mov_b64_e32 v[136:137], s[0:1]
	v_ashrrev_i32_e32 v135, 31, v134
	s_waitcnt vmcnt(7)
	v_pk_fma_f32 v[132:133], v[138:139], s[86:87], v[136:137] op_sel_hi:[1,0,0]
	v_rsq_f32_e32 v167, v132
	s_nop 0
	v_mul_f32_e32 v122, v122, v167
	v_mul_f32_e32 v126, v126, v167
	v_mul_f32_e32 v114, v114, v167
	v_rsq_f32_e32 v166, v133
	v_pk_fma_f32 v[132:133], v[140:141], s[86:87], v[136:137] op_sel_hi:[1,0,0]
	v_mul_f32_e32 v118, v118, v167
	v_rsq_f32_e32 v165, v132
	v_rsq_f32_e32 v163, v133
	s_waitcnt vmcnt(6)
	v_pk_fma_f32 v[132:133], v[176:177], s[86:87], v[136:137] op_sel_hi:[1,0,0]
	v_rsq_f32_e32 v164, v132
	v_rsq_f32_e32 v162, v133
	v_pk_fma_f32 v[132:133], v[178:179], s[86:87], v[136:137] op_sel_hi:[1,0,0]
	v_rsq_f32_e32 v161, v132
	v_rsq_f32_e32 v159, v133
	s_waitcnt vmcnt(5)
	v_pk_fma_f32 v[132:133], v[180:181], s[86:87], v[136:137] op_sel_hi:[1,0,0]
	v_rsq_f32_e32 v160, v132
	v_rsq_f32_e32 v158, v133
	v_pk_fma_f32 v[132:133], v[182:183], s[86:87], v[136:137] op_sel_hi:[1,0,0]
	v_rsq_f32_e32 v157, v132
	v_rsq_f32_e32 v155, v133
	s_waitcnt vmcnt(4)
	v_pk_fma_f32 v[132:133], v[184:185], s[86:87], v[136:137] op_sel_hi:[1,0,0]
	v_rsq_f32_e32 v156, v132
	v_rsq_f32_e32 v154, v133
	v_pk_fma_f32 v[132:133], v[186:187], s[86:87], v[136:137] op_sel_hi:[1,0,0]
	v_rsq_f32_e32 v153, v132
	v_rsq_f32_e32 v150, v133
	s_waitcnt vmcnt(3)
	v_pk_fma_f32 v[132:133], v[188:189], s[86:87], v[136:137] op_sel_hi:[1,0,0]
	v_rsq_f32_e32 v151, v132
	v_rsq_f32_e32 v148, v133
	v_pk_fma_f32 v[132:133], v[190:191], s[86:87], v[136:137] op_sel_hi:[1,0,0]
	v_rsq_f32_e32 v146, v132
	v_rsq_f32_e32 v143, v133
	s_waitcnt vmcnt(2)
	v_pk_fma_f32 v[132:133], v[192:193], s[86:87], v[136:137] op_sel_hi:[1,0,0]
	v_rsq_f32_e32 v145, v132
	v_rsq_f32_e32 v142, v133
	v_pk_fma_f32 v[132:133], v[194:195], s[86:87], v[136:137] op_sel_hi:[1,0,0]
	v_rsq_f32_e32 v140, v132
	v_rsq_f32_e32 v138, v133
	s_waitcnt vmcnt(1)
	v_pk_fma_f32 v[132:133], v[170:171], s[86:87], v[136:137] op_sel_hi:[1,0,0]
	v_rsq_f32_e32 v147, v132
	v_rsq_f32_e32 v144, v133
	v_pk_fma_f32 v[132:133], v[172:173], s[86:87], v[136:137] op_sel_hi:[1,0,0]
	v_rsq_f32_e32 v141, v132
	v_rsq_f32_e32 v139, v133
	s_waitcnt vmcnt(0)
; DI bf16_t to_bf16(float x) { return (bf16_t)(pack_bf16(x, 0.f) & 0xffffu); }
;   DI void run8(f32x4 (&acc)[8][4], int rb, int cb, int fr, int fq) const {
;     ...
;       for (int j = 0; j < 4; ++j) rsv[m][j] = rsqrtf(ssq[rb + m * 16 + fq * 4 + j] * (1.f / D) + EPS);
; #pragma unroll
;     for (int m = 0; m < 8; ++m) {
; #pragma unroll
;       for (int j = 0; j < 4; ++j)
; #pragma unroll
;         for (int pi = 0; pi < 2; ++pi) {
;           const float g = acc[m][2 * pi][j] * rsv[m][j], u = acc[m][2 * pi + 1][j] * rsv[m][j];
;           const float a = g * __builtin_amdgcn_rcpf(1.f + __expf(-g)) * u;
;           scr[(fq * 4 + j) * 40 + pi * 16 + fr] = to_bf16(a);
;         }
;       __builtin_amdgcn_sched_barrier(0);
;       const u32x4 o = *(const u32x4*)(scr + srow * 40 + sch * 8);
;       *(u32x4*)(ap + (size_t)(m * 16) * LDA) = o;
;       __builtin_amdgcn_sched_barrier(0);
;     }
	v_pk_fma_f32 v[130:131], v[196:197], s[86:87], v[136:137] op_sel_hi:[1,0,0]
	v_rsq_f32_e32 v152, v130
	v_rsq_f32_e32 v149, v131
	v_pk_fma_f32 v[130:131], v[198:199], s[86:87], v[136:137] op_sel_hi:[1,0,0]
	v_rsq_f32_e32 v136, v130
	s_movk_i32 s0, 0x1680
	v_lshlrev_b32_e32 v132, 1, v223
	v_rsq_f32_e32 v133, v131
	v_mov_b64_e32 v[130:131], s[52:53]
	v_mad_i64_i32 v[130:131], s[0:1], v0, s0, v[130:131]
	v_lshlrev_b32_e32 v0, 4, v223
	v_lshl_add_u64 v[130:131], v[134:135], 1, v[130:131]
	v_and_b32_e32 v0, 48, v0
	v_mul_u32_u24_e32 v134, 0x50, v222
	v_lshl_add_u64 v[130:131], v[130:131], 0, v[0:1]
	v_add3_u32 v0, v217, v134, v0
	v_mul_u32_u24_e32 v134, 0x140, v168
	v_add3_u32 v132, v217, v132, v134
	v_mul_f32_e32 v134, 0xbfb8aa3b, v122
	v_exp_f32_e32 v134, v134
	s_nop 0
	v_add_f32_e32 v134, 1.0, v134
	v_rcp_f32_e32 v134, v134
	s_nop 0
	v_mul_f32_e32 v122, v122, v134
	v_mul_f32_e32 v122, v126, v122
	v_cvt_pk_bf16_f32 v122, v122, s0
	ds_write_b16 v132, v122
	v_mul_f32_e32 v122, 0xbfb8aa3b, v114
	v_exp_f32_e32 v122, v122
	s_nop 0
	v_add_f32_e32 v122, 1.0, v122
	v_rcp_f32_e32 v122, v122
	s_nop 0
	v_mul_f32_e32 v114, v114, v122
	v_mul_f32_e32 v114, v118, v114
	v_cvt_pk_bf16_f32 v114, v114, s0
	ds_write_b16 v132, v114 offset:32
	v_mul_f32_e32 v114, v123, v166
	v_mul_f32_e32 v122, 0xbfb8aa3b, v114
	v_exp_f32_e32 v122, v122
	v_mul_f32_e32 v118, v127, v166
	v_add_f32_e32 v122, 1.0, v122
	v_rcp_f32_e32 v122, v122
	s_nop 0
	v_mul_f32_e32 v114, v114, v122
	v_mul_f32_e32 v114, v118, v114
	v_cvt_pk_bf16_f32 v114, v114, s0
	ds_write_b16 v132, v114 offset:80
	v_mul_f32_e32 v114, v115, v166
	v_mul_f32_e32 v118, 0xbfb8aa3b, v114
	v_exp_f32_e32 v118, v118
	v_mul_f32_e32 v115, v119, v166
	v_add_f32_e32 v118, 1.0, v118
	v_rcp_f32_e32 v118, v118
	s_nop 0
	v_mul_f32_e32 v114, v114, v118
	v_mul_f32_e32 v114, v115, v114
	v_cvt_pk_bf16_f32 v114, v114, s0
	ds_write_b16 v132, v114 offset:112
	v_mul_f32_e32 v114, v124, v165
	v_mul_f32_e32 v118, 0xbfb8aa3b, v114
	v_exp_f32_e32 v118, v118
	v_mul_f32_e32 v115, v128, v165
	v_add_f32_e32 v118, 1.0, v118
	v_rcp_f32_e32 v118, v118
	s_nop 0
	v_mul_f32_e32 v114, v114, v118
	v_mul_f32_e32 v114, v115, v114
	v_cvt_pk_bf16_f32 v114, v114, s0
	ds_write_b16 v132, v114 offset:160
	v_mul_f32_e32 v114, v116, v165
	v_mul_f32_e32 v116, 0xbfb8aa3b, v114
	v_exp_f32_e32 v116, v116
	v_mul_f32_e32 v115, v120, v165
	v_add_f32_e32 v116, 1.0, v116
	v_rcp_f32_e32 v116, v116
	s_nop 0
	v_mul_f32_e32 v114, v114, v116
	v_mul_f32_e32 v114, v115, v114
	v_cvt_pk_bf16_f32 v114, v114, s0
	ds_write_b16 v132, v114 offset:192
	v_mul_f32_e32 v114, v125, v163
	v_mul_f32_e32 v116, 0xbfb8aa3b, v114
	v_exp_f32_e32 v116, v116
	v_mul_f32_e32 v115, v129, v163
	v_add_f32_e32 v116, 1.0, v116
	v_rcp_f32_e32 v116, v116
	s_nop 0
	v_mul_f32_e32 v114, v114, v116
	v_mul_f32_e32 v114, v115, v114
	v_cvt_pk_bf16_f32 v114, v114, s0
	ds_write_b16 v132, v114 offset:240
	v_mul_f32_e32 v114, v117, v163
	v_mul_f32_e32 v116, 0xbfb8aa3b, v114
	v_exp_f32_e32 v116, v116
	v_mul_f32_e32 v115, v121, v163
	v_add_f32_e32 v116, 1.0, v116
	v_rcp_f32_e32 v116, v116
	s_nop 0
	v_mul_f32_e32 v114, v114, v116
	v_mul_f32_e32 v114, v115, v114
	v_cvt_pk_bf16_f32 v114, v114, s0
	ds_write_b16 v132, v114 offset:272
	ds_read_b128 v[114:117], v0
	s_waitcnt lgkmcnt(0)
	global_store_dwordx4 v[130:131], v[114:117], off
	v_mul_f32_e32 v106, v106, v164
	s_nop 0
	v_mul_f32_e32 v114, 0xbfb8aa3b, v106
	v_exp_f32_e32 v114, v114
	v_mul_f32_e32 v110, v110, v164
	v_mul_f32_e32 v98, v98, v164
	v_mul_f32_e32 v102, v102, v164
	v_add_f32_e32 v114, 1.0, v114
	v_rcp_f32_e32 v114, v114
	s_nop 0
	v_mul_f32_e32 v106, v106, v114
	v_mul_f32_e32 v106, v110, v106
	v_cvt_pk_bf16_f32 v106, v106, s0
	ds_write_b16 v132, v106
	v_mul_f32_e32 v106, 0xbfb8aa3b, v98
	v_exp_f32_e32 v106, v106
	s_nop 0
	v_add_f32_e32 v106, 1.0, v106
	v_rcp_f32_e32 v106, v106
	s_nop 0
	v_mul_f32_e32 v98, v98, v106
	v_mul_f32_e32 v98, v102, v98
	v_cvt_pk_bf16_f32 v98, v98, s0
	ds_write_b16 v132, v98 offset:32
	v_mul_f32_e32 v98, v107, v162
	v_mul_f32_e32 v106, 0xbfb8aa3b, v98
	v_exp_f32_e32 v106, v106
	v_mul_f32_e32 v102, v111, v162
	v_add_f32_e32 v106, 1.0, v106
	v_rcp_f32_e32 v106, v106
	s_nop 0
	v_mul_f32_e32 v98, v98, v106
	v_mul_f32_e32 v98, v102, v98
	v_cvt_pk_bf16_f32 v98, v98, s0
	ds_write_b16 v132, v98 offset:80
	v_mul_f32_e32 v98, v99, v162
	v_mul_f32_e32 v102, 0xbfb8aa3b, v98
	v_exp_f32_e32 v102, v102
	v_mul_f32_e32 v99, v103, v162
	v_add_f32_e32 v102, 1.0, v102
	v_rcp_f32_e32 v102, v102
	s_nop 0
	v_mul_f32_e32 v98, v98, v102
	v_mul_f32_e32 v98, v99, v98
	v_cvt_pk_bf16_f32 v98, v98, s0
	ds_write_b16 v132, v98 offset:112
	v_mul_f32_e32 v98, v108, v161
	v_mul_f32_e32 v102, 0xbfb8aa3b, v98
	v_exp_f32_e32 v102, v102
	v_mul_f32_e32 v99, v112, v161
	v_add_f32_e32 v102, 1.0, v102
	v_rcp_f32_e32 v102, v102
	s_nop 0
	v_mul_f32_e32 v98, v98, v102
	v_mul_f32_e32 v98, v99, v98
	v_cvt_pk_bf16_f32 v98, v98, s0
	ds_write_b16 v132, v98 offset:160
	v_mul_f32_e32 v98, v100, v161
	v_mul_f32_e32 v100, 0xbfb8aa3b, v98
	v_exp_f32_e32 v100, v100
	v_mul_f32_e32 v99, v104, v161
	v_add_f32_e32 v100, 1.0, v100
	v_rcp_f32_e32 v100, v100
	s_nop 0
	v_mul_f32_e32 v98, v98, v100
	v_mul_f32_e32 v98, v99, v98
	v_cvt_pk_bf16_f32 v98, v98, s0
	ds_write_b16 v132, v98 offset:192
	v_mul_f32_e32 v98, v109, v159
	v_mul_f32_e32 v100, 0xbfb8aa3b, v98
	v_exp_f32_e32 v100, v100
	v_mul_f32_e32 v99, v113, v159
	v_add_f32_e32 v100, 1.0, v100
	v_rcp_f32_e32 v100, v100
	s_nop 0
	v_mul_f32_e32 v98, v98, v100
	v_mul_f32_e32 v98, v99, v98
	v_cvt_pk_bf16_f32 v98, v98, s0
	ds_write_b16 v132, v98 offset:240
	v_mul_f32_e32 v98, v101, v159
	v_mul_f32_e32 v100, 0xbfb8aa3b, v98
	v_exp_f32_e32 v100, v100
	v_mul_f32_e32 v99, v105, v159
	v_add_f32_e32 v100, 1.0, v100
	v_rcp_f32_e32 v100, v100
	s_nop 0
	v_mul_f32_e32 v98, v98, v100
	v_mul_f32_e32 v98, v99, v98
	v_cvt_pk_bf16_f32 v98, v98, s0
	ds_write_b16 v132, v98 offset:272
	ds_read_b128 v[98:101], v0
	s_mov_b32 s0, 0x16000
	v_add_co_u32_e32 v102, vcc, s0, v130
	s_nop 1
	v_addc_co_u32_e32 v103, vcc, 0, v131, vcc
	s_waitcnt lgkmcnt(0)
; DI bf16_t to_bf16(float x) { return (bf16_t)(pack_bf16(x, 0.f) & 0xffffu); }
;   DI void run8(f32x4 (&acc)[8][4], int rb, int cb, int fr, int fq) const {
;     ...
;     for (int m = 0; m < 8; ++m) {
; #pragma unroll
;       for (int j = 0; j < 4; ++j)
; #pragma unroll
;         for (int pi = 0; pi < 2; ++pi) {
;           const float g = acc[m][2 * pi][j] * rsv[m][j], u = acc[m][2 * pi + 1][j] * rsv[m][j];
;           const float a = g * __builtin_amdgcn_rcpf(1.f + __expf(-g)) * u;
;           scr[(fq * 4 + j) * 40 + pi * 16 + fr] = to_bf16(a);
;         }
;       __builtin_amdgcn_sched_barrier(0);
;       const u32x4 o = *(const u32x4*)(scr + srow * 40 + sch * 8);
;       *(u32x4*)(ap + (size_t)(m * 16) * LDA) = o;
;       __builtin_amdgcn_sched_barrier(0);
;     }
	global_store_dwordx4 v[102:103], v[98:101], off offset:2048
	v_mul_f32_e32 v90, v90, v160
	s_nop 0
	v_mul_f32_e32 v98, 0xbfb8aa3b, v90
	v_exp_f32_e32 v98, v98
	v_mul_f32_e32 v94, v94, v160
	v_mul_f32_e32 v82, v82, v160
	v_mul_f32_e32 v86, v86, v160
	v_add_f32_e32 v98, 1.0, v98
	v_rcp_f32_e32 v98, v98
	s_nop 0
	v_mul_f32_e32 v90, v90, v98
	v_mul_f32_e32 v90, v94, v90
	v_cvt_pk_bf16_f32 v90, v90, s0
	ds_write_b16 v132, v90
	v_mul_f32_e32 v90, 0xbfb8aa3b, v82
	v_exp_f32_e32 v90, v90
	s_nop 0
	v_add_f32_e32 v90, 1.0, v90
	v_rcp_f32_e32 v90, v90
	s_nop 0
	v_mul_f32_e32 v82, v82, v90
	v_mul_f32_e32 v82, v86, v82
	v_cvt_pk_bf16_f32 v82, v82, s0
	ds_write_b16 v132, v82 offset:32
	v_mul_f32_e32 v82, v91, v158
	v_mul_f32_e32 v90, 0xbfb8aa3b, v82
	v_exp_f32_e32 v90, v90
	v_mul_f32_e32 v86, v95, v158
	v_add_f32_e32 v90, 1.0, v90
	v_rcp_f32_e32 v90, v90
	s_nop 0
	v_mul_f32_e32 v82, v82, v90
	v_mul_f32_e32 v82, v86, v82
	v_cvt_pk_bf16_f32 v82, v82, s0
	ds_write_b16 v132, v82 offset:80
	v_mul_f32_e32 v82, v83, v158
	v_mul_f32_e32 v86, 0xbfb8aa3b, v82
	v_exp_f32_e32 v86, v86
	v_mul_f32_e32 v83, v87, v158
	v_add_f32_e32 v86, 1.0, v86
	v_rcp_f32_e32 v86, v86
	s_nop 0
	v_mul_f32_e32 v82, v82, v86
	v_mul_f32_e32 v82, v83, v82
	v_cvt_pk_bf16_f32 v82, v82, s0
	ds_write_b16 v132, v82 offset:112
	v_mul_f32_e32 v82, v92, v157
	v_mul_f32_e32 v86, 0xbfb8aa3b, v82
	v_exp_f32_e32 v86, v86
	v_mul_f32_e32 v83, v96, v157
	v_add_f32_e32 v86, 1.0, v86
	v_rcp_f32_e32 v86, v86
	s_nop 0
	v_mul_f32_e32 v82, v82, v86
	v_mul_f32_e32 v82, v83, v82
	v_cvt_pk_bf16_f32 v82, v82, s0
	ds_write_b16 v132, v82 offset:160
	v_mul_f32_e32 v82, v84, v157
	v_mul_f32_e32 v84, 0xbfb8aa3b, v82
	v_exp_f32_e32 v84, v84
	v_mul_f32_e32 v83, v88, v157
	v_add_f32_e32 v84, 1.0, v84
	v_rcp_f32_e32 v84, v84
	s_nop 0
	v_mul_f32_e32 v82, v82, v84
	v_mul_f32_e32 v82, v83, v82
	v_cvt_pk_bf16_f32 v82, v82, s0
	ds_write_b16 v132, v82 offset:192
	v_mul_f32_e32 v82, v93, v155
	v_mul_f32_e32 v84, 0xbfb8aa3b, v82
	v_exp_f32_e32 v84, v84
	v_mul_f32_e32 v83, v97, v155
	v_add_f32_e32 v84, 1.0, v84
	v_rcp_f32_e32 v84, v84
	s_nop 0
	v_mul_f32_e32 v82, v82, v84
	v_mul_f32_e32 v82, v83, v82
	v_cvt_pk_bf16_f32 v82, v82, s0
	ds_write_b16 v132, v82 offset:240
	v_mul_f32_e32 v82, v85, v155
	v_mul_f32_e32 v84, 0xbfb8aa3b, v82
	v_exp_f32_e32 v84, v84
	v_mul_f32_e32 v83, v89, v155
	v_add_f32_e32 v84, 1.0, v84
	v_rcp_f32_e32 v84, v84
	s_nop 0
	v_mul_f32_e32 v82, v82, v84
	v_mul_f32_e32 v82, v83, v82
	v_cvt_pk_bf16_f32 v82, v82, s0
	ds_write_b16 v132, v82 offset:272
	ds_read_b128 v[82:85], v0
	s_mov_b32 s0, 0x2d000
	v_add_co_u32_e32 v86, vcc, s0, v130
	s_nop 1
	v_addc_co_u32_e32 v87, vcc, 0, v131, vcc
	s_waitcnt lgkmcnt(0)
	global_store_dwordx4 v[86:87], v[82:85], off
	v_mul_f32_e32 v74, v74, v156
	s_nop 0
	v_mul_f32_e32 v82, 0xbfb8aa3b, v74
	v_exp_f32_e32 v82, v82
	v_mul_f32_e32 v78, v78, v156
	v_mul_f32_e32 v66, v66, v156
	v_mul_f32_e32 v70, v70, v156
	v_add_f32_e32 v82, 1.0, v82
	v_rcp_f32_e32 v82, v82
	s_nop 0
	v_mul_f32_e32 v74, v74, v82
	v_mul_f32_e32 v74, v78, v74
	v_cvt_pk_bf16_f32 v74, v74, s0
	ds_write_b16 v132, v74
	v_mul_f32_e32 v74, 0xbfb8aa3b, v66
	v_exp_f32_e32 v74, v74
	s_nop 0
	v_add_f32_e32 v74, 1.0, v74
	v_rcp_f32_e32 v74, v74
	s_nop 0
	v_mul_f32_e32 v66, v66, v74
	v_mul_f32_e32 v66, v70, v66
	v_cvt_pk_bf16_f32 v66, v66, s0
	ds_write_b16 v132, v66 offset:32
	v_mul_f32_e32 v66, v75, v154
	v_mul_f32_e32 v74, 0xbfb8aa3b, v66
	v_exp_f32_e32 v74, v74
	v_mul_f32_e32 v70, v79, v154
	v_add_f32_e32 v74, 1.0, v74
	v_rcp_f32_e32 v74, v74
	s_nop 0
	v_mul_f32_e32 v66, v66, v74
	v_mul_f32_e32 v66, v70, v66
	v_cvt_pk_bf16_f32 v66, v66, s0
	ds_write_b16 v132, v66 offset:80
	v_mul_f32_e32 v66, v67, v154
	v_mul_f32_e32 v70, 0xbfb8aa3b, v66
	v_exp_f32_e32 v70, v70
	v_mul_f32_e32 v67, v71, v154
	v_add_f32_e32 v70, 1.0, v70
	v_rcp_f32_e32 v70, v70
	s_nop 0
	v_mul_f32_e32 v66, v66, v70
	v_mul_f32_e32 v66, v67, v66
	v_cvt_pk_bf16_f32 v66, v66, s0
	ds_write_b16 v132, v66 offset:112
	v_mul_f32_e32 v66, v76, v153
	v_mul_f32_e32 v70, 0xbfb8aa3b, v66
	v_exp_f32_e32 v70, v70
	v_mul_f32_e32 v67, v80, v153
	v_add_f32_e32 v70, 1.0, v70
	v_rcp_f32_e32 v70, v70
	s_nop 0
	v_mul_f32_e32 v66, v66, v70
	v_mul_f32_e32 v66, v67, v66
	v_cvt_pk_bf16_f32 v66, v66, s0
	ds_write_b16 v132, v66 offset:160
	v_mul_f32_e32 v66, v68, v153
	v_mul_f32_e32 v68, 0xbfb8aa3b, v66
	v_exp_f32_e32 v68, v68
	v_mul_f32_e32 v67, v72, v153
	v_add_f32_e32 v68, 1.0, v68
	v_rcp_f32_e32 v68, v68
	s_nop 0
	v_mul_f32_e32 v66, v66, v68
	v_mul_f32_e32 v66, v67, v66
	v_cvt_pk_bf16_f32 v66, v66, s0
	ds_write_b16 v132, v66 offset:192
	v_mul_f32_e32 v66, v77, v150
	v_mul_f32_e32 v68, 0xbfb8aa3b, v66
	v_exp_f32_e32 v68, v68
	v_mul_f32_e32 v67, v81, v150
	v_add_f32_e32 v68, 1.0, v68
	v_rcp_f32_e32 v68, v68
	s_nop 0
	v_mul_f32_e32 v66, v66, v68
	v_mul_f32_e32 v66, v67, v66
	v_cvt_pk_bf16_f32 v66, v66, s0
	ds_write_b16 v132, v66 offset:240
	v_mul_f32_e32 v66, v69, v150
	v_mul_f32_e32 v68, 0xbfb8aa3b, v66
	v_exp_f32_e32 v68, v68
	v_mul_f32_e32 v67, v73, v150
	v_add_f32_e32 v68, 1.0, v68
	v_rcp_f32_e32 v68, v68
	s_nop 0
	v_mul_f32_e32 v66, v66, v68
	v_mul_f32_e32 v66, v67, v66
	v_cvt_pk_bf16_f32 v66, v66, s0
	ds_write_b16 v132, v66 offset:272
	ds_read_b128 v[66:69], v0
	s_mov_b32 s0, 0x43000
	v_add_co_u32_e32 v70, vcc, s0, v130
	s_nop 1
	v_addc_co_u32_e32 v71, vcc, 0, v131, vcc
	s_waitcnt lgkmcnt(0)
; DI bf16_t to_bf16(float x) { return (bf16_t)(pack_bf16(x, 0.f) & 0xffffu); }
;   DI void run8(f32x4 (&acc)[8][4], int rb, int cb, int fr, int fq) const {
;     ...
;     for (int m = 0; m < 8; ++m) {
; #pragma unroll
;       for (int j = 0; j < 4; ++j)
; #pragma unroll
;         for (int pi = 0; pi < 2; ++pi) {
;           const float g = acc[m][2 * pi][j] * rsv[m][j], u = acc[m][2 * pi + 1][j] * rsv[m][j];
;           const float a = g * __builtin_amdgcn_rcpf(1.f + __expf(-g)) * u;
;           scr[(fq * 4 + j) * 40 + pi * 16 + fr] = to_bf16(a);
;         }
;       __builtin_amdgcn_sched_barrier(0);
;       const u32x4 o = *(const u32x4*)(scr + srow * 40 + sch * 8);
;       *(u32x4*)(ap + (size_t)(m * 16) * LDA) = o;
;       __builtin_amdgcn_sched_barrier(0);
;     }
	global_store_dwordx4 v[70:71], v[66:69], off offset:2048
	v_mul_f32_e32 v58, v58, v151
	s_nop 0
	v_mul_f32_e32 v66, 0xbfb8aa3b, v58
	v_exp_f32_e32 v66, v66
	v_mul_f32_e32 v62, v62, v151
	v_mul_f32_e32 v50, v50, v151
	v_mul_f32_e32 v54, v54, v151
	v_add_f32_e32 v66, 1.0, v66
	v_rcp_f32_e32 v66, v66
	s_nop 0
	v_mul_f32_e32 v58, v58, v66
	v_mul_f32_e32 v58, v62, v58
	v_cvt_pk_bf16_f32 v58, v58, s0
	ds_write_b16 v132, v58
	v_mul_f32_e32 v58, 0xbfb8aa3b, v50
	v_exp_f32_e32 v58, v58
	s_nop 0
	v_add_f32_e32 v58, 1.0, v58
	v_rcp_f32_e32 v58, v58
	s_nop 0
	v_mul_f32_e32 v50, v50, v58
	v_mul_f32_e32 v50, v54, v50
	v_cvt_pk_bf16_f32 v50, v50, s0
	ds_write_b16 v132, v50 offset:32
	v_mul_f32_e32 v50, v59, v148
	v_mul_f32_e32 v58, 0xbfb8aa3b, v50
	v_exp_f32_e32 v58, v58
	v_mul_f32_e32 v54, v63, v148
	v_add_f32_e32 v58, 1.0, v58
	v_rcp_f32_e32 v58, v58
	s_nop 0
	v_mul_f32_e32 v50, v50, v58
	v_mul_f32_e32 v50, v54, v50
	v_cvt_pk_bf16_f32 v50, v50, s0
	ds_write_b16 v132, v50 offset:80
	v_mul_f32_e32 v50, v51, v148
	v_mul_f32_e32 v54, 0xbfb8aa3b, v50
	v_exp_f32_e32 v54, v54
	v_mul_f32_e32 v51, v55, v148
	v_add_f32_e32 v54, 1.0, v54
	v_rcp_f32_e32 v54, v54
	s_nop 0
	v_mul_f32_e32 v50, v50, v54
	v_mul_f32_e32 v50, v51, v50
	v_cvt_pk_bf16_f32 v50, v50, s0
	ds_write_b16 v132, v50 offset:112
	v_mul_f32_e32 v50, v60, v146
	v_mul_f32_e32 v54, 0xbfb8aa3b, v50
	v_exp_f32_e32 v54, v54
	v_mul_f32_e32 v51, v64, v146
	v_add_f32_e32 v54, 1.0, v54
	v_rcp_f32_e32 v54, v54
	s_nop 0
	v_mul_f32_e32 v50, v50, v54
	v_mul_f32_e32 v50, v51, v50
	v_cvt_pk_bf16_f32 v50, v50, s0
	ds_write_b16 v132, v50 offset:160
	v_mul_f32_e32 v50, v52, v146
	v_mul_f32_e32 v52, 0xbfb8aa3b, v50
	v_exp_f32_e32 v52, v52
	v_mul_f32_e32 v51, v56, v146
	v_add_f32_e32 v52, 1.0, v52
	v_rcp_f32_e32 v52, v52
	s_nop 0
	v_mul_f32_e32 v50, v50, v52
	v_mul_f32_e32 v50, v51, v50
	v_cvt_pk_bf16_f32 v50, v50, s0
	ds_write_b16 v132, v50 offset:192
	v_mul_f32_e32 v50, v61, v143
	v_mul_f32_e32 v52, 0xbfb8aa3b, v50
	v_exp_f32_e32 v52, v52
	v_mul_f32_e32 v51, v65, v143
	v_add_f32_e32 v52, 1.0, v52
	v_rcp_f32_e32 v52, v52
	s_nop 0
	v_mul_f32_e32 v50, v50, v52
	v_mul_f32_e32 v50, v51, v50
	v_cvt_pk_bf16_f32 v50, v50, s0
	ds_write_b16 v132, v50 offset:240
	v_mul_f32_e32 v50, v53, v143
	v_mul_f32_e32 v52, 0xbfb8aa3b, v50
	v_exp_f32_e32 v52, v52
	v_mul_f32_e32 v51, v57, v143
	v_add_f32_e32 v52, 1.0, v52
	v_rcp_f32_e32 v52, v52
	s_nop 0
	v_mul_f32_e32 v50, v50, v52
	v_mul_f32_e32 v50, v51, v50
	v_cvt_pk_bf16_f32 v50, v50, s0
	ds_write_b16 v132, v50 offset:272
	ds_read_b128 v[50:53], v0
	s_mov_b32 s0, 0x5a000
	v_add_co_u32_e32 v54, vcc, s0, v130
	s_nop 1
	v_addc_co_u32_e32 v55, vcc, 0, v131, vcc
	s_waitcnt lgkmcnt(0)
	global_store_dwordx4 v[54:55], v[50:53], off
	v_mul_f32_e32 v42, v42, v145
	s_nop 0
	v_mul_f32_e32 v50, 0xbfb8aa3b, v42
	v_exp_f32_e32 v50, v50
	v_mul_f32_e32 v46, v46, v145
	v_mul_f32_e32 v34, v34, v145
	v_mul_f32_e32 v38, v38, v145
	v_add_f32_e32 v50, 1.0, v50
	v_rcp_f32_e32 v50, v50
	s_nop 0
	v_mul_f32_e32 v42, v42, v50
	v_mul_f32_e32 v42, v46, v42
	v_cvt_pk_bf16_f32 v42, v42, s0
	ds_write_b16 v132, v42
	v_mul_f32_e32 v42, 0xbfb8aa3b, v34
	v_exp_f32_e32 v42, v42
	s_nop 0
	v_add_f32_e32 v42, 1.0, v42
	v_rcp_f32_e32 v42, v42
	s_nop 0
	v_mul_f32_e32 v34, v34, v42
	v_mul_f32_e32 v34, v38, v34
	v_cvt_pk_bf16_f32 v34, v34, s0
	ds_write_b16 v132, v34 offset:32
	v_mul_f32_e32 v34, v43, v142
	v_mul_f32_e32 v42, 0xbfb8aa3b, v34
	v_exp_f32_e32 v42, v42
	v_mul_f32_e32 v38, v47, v142
	v_add_f32_e32 v42, 1.0, v42
	v_rcp_f32_e32 v42, v42
	s_nop 0
	v_mul_f32_e32 v34, v34, v42
	v_mul_f32_e32 v34, v38, v34
	v_cvt_pk_bf16_f32 v34, v34, s0
	ds_write_b16 v132, v34 offset:80
	v_mul_f32_e32 v34, v35, v142
	v_mul_f32_e32 v38, 0xbfb8aa3b, v34
	v_exp_f32_e32 v38, v38
	v_mul_f32_e32 v35, v39, v142
	v_add_f32_e32 v38, 1.0, v38
	v_rcp_f32_e32 v38, v38
	s_nop 0
	v_mul_f32_e32 v34, v34, v38
	v_mul_f32_e32 v34, v35, v34
	v_cvt_pk_bf16_f32 v34, v34, s0
	ds_write_b16 v132, v34 offset:112
	v_mul_f32_e32 v34, v44, v140
	v_mul_f32_e32 v38, 0xbfb8aa3b, v34
	v_exp_f32_e32 v38, v38
	v_mul_f32_e32 v35, v48, v140
	v_add_f32_e32 v38, 1.0, v38
	v_rcp_f32_e32 v38, v38
	s_nop 0
	v_mul_f32_e32 v34, v34, v38
	v_mul_f32_e32 v34, v35, v34
	v_cvt_pk_bf16_f32 v34, v34, s0
	ds_write_b16 v132, v34 offset:160
	v_mul_f32_e32 v34, v36, v140
	v_mul_f32_e32 v36, 0xbfb8aa3b, v34
	v_exp_f32_e32 v36, v36
	v_mul_f32_e32 v35, v40, v140
	v_add_f32_e32 v36, 1.0, v36
	v_rcp_f32_e32 v36, v36
	s_nop 0
	v_mul_f32_e32 v34, v34, v36
	v_mul_f32_e32 v34, v35, v34
	v_cvt_pk_bf16_f32 v34, v34, s0
	ds_write_b16 v132, v34 offset:192
	v_mul_f32_e32 v34, v45, v138
	v_mul_f32_e32 v36, 0xbfb8aa3b, v34
	v_exp_f32_e32 v36, v36
	v_mul_f32_e32 v35, v49, v138
	v_add_f32_e32 v36, 1.0, v36
	v_rcp_f32_e32 v36, v36
	s_nop 0
	v_mul_f32_e32 v34, v34, v36
	v_mul_f32_e32 v34, v35, v34
	v_cvt_pk_bf16_f32 v34, v34, s0
	ds_write_b16 v132, v34 offset:240
	v_mul_f32_e32 v34, v37, v138
	v_mul_f32_e32 v36, 0xbfb8aa3b, v34
	v_exp_f32_e32 v36, v36
	v_mul_f32_e32 v35, v41, v138
	v_add_f32_e32 v36, 1.0, v36
	v_rcp_f32_e32 v36, v36
	s_nop 0
	v_mul_f32_e32 v34, v34, v36
	v_mul_f32_e32 v34, v35, v34
	v_cvt_pk_bf16_f32 v34, v34, s0
	ds_write_b16 v132, v34 offset:272
	ds_read_b128 v[34:37], v0
	v_add_co_u32_e32 v38, vcc, s68, v130
	s_nop 1
	v_addc_co_u32_e32 v39, vcc, 0, v131, vcc
	s_waitcnt lgkmcnt(0)
; DI bf16_t to_bf16(float x) { return (bf16_t)(pack_bf16(x, 0.f) & 0xffffu); }
; template <class Epi>
; DI void gemm8_tile(const bf16_t* __restrict__ Ab, int lda, const bf16_t* __restrict__ Bb, int ldb, int K, int brow, int bcol, const Epi epi,
;                    bool staged, bool has_next, const bf16_t* __restrict__ Abn, const bf16_t* __restrict__ Bbn) {
;     ...
;   if (Epi::LDS_SCRATCH) __syncthreads();
;   DI void run8(f32x4 (&acc)[8][4], int rb, int cb, int fr, int fq) const {
;     ...
;     for (int m = 0; m < 8; ++m) {
; #pragma unroll
;       for (int j = 0; j < 4; ++j)
; #pragma unroll
;         for (int pi = 0; pi < 2; ++pi) {
;           const float g = acc[m][2 * pi][j] * rsv[m][j], u = acc[m][2 * pi + 1][j] * rsv[m][j];
;           const float a = g * __builtin_amdgcn_rcpf(1.f + __expf(-g)) * u;
;           scr[(fq * 4 + j) * 40 + pi * 16 + fr] = to_bf16(a);
;         }
;       __builtin_amdgcn_sched_barrier(0);
;       const u32x4 o = *(const u32x4*)(scr + srow * 40 + sch * 8);
;       *(u32x4*)(ap + (size_t)(m * 16) * LDA) = o;
;       __builtin_amdgcn_sched_barrier(0);
;     }
	global_store_dwordx4 v[38:39], v[34:37], off offset:2048
	v_mul_f32_e32 v26, v26, v147
	s_nop 0
	v_mul_f32_e32 v34, 0xbfb8aa3b, v26
	v_exp_f32_e32 v34, v34
	v_mul_f32_e32 v30, v30, v147
	v_mul_f32_e32 v18, v18, v147
	v_mul_f32_e32 v22, v22, v147
	v_add_f32_e32 v34, 1.0, v34
	v_rcp_f32_e32 v34, v34
	s_nop 0
	v_mul_f32_e32 v26, v26, v34
	v_mul_f32_e32 v26, v30, v26
	v_cvt_pk_bf16_f32 v26, v26, s0
	ds_write_b16 v132, v26
	v_mul_f32_e32 v26, 0xbfb8aa3b, v18
	v_exp_f32_e32 v26, v26
	s_nop 0
	v_add_f32_e32 v26, 1.0, v26
	v_rcp_f32_e32 v26, v26
	s_nop 0
	v_mul_f32_e32 v18, v18, v26
	v_mul_f32_e32 v18, v22, v18
	v_cvt_pk_bf16_f32 v18, v18, s0
	ds_write_b16 v132, v18 offset:32
	v_mul_f32_e32 v18, v27, v144
	v_mul_f32_e32 v26, 0xbfb8aa3b, v18
	v_exp_f32_e32 v26, v26
	v_mul_f32_e32 v22, v31, v144
	v_add_f32_e32 v26, 1.0, v26
	v_rcp_f32_e32 v26, v26
	s_nop 0
	v_mul_f32_e32 v18, v18, v26
	v_mul_f32_e32 v18, v22, v18
	v_cvt_pk_bf16_f32 v18, v18, s0
	ds_write_b16 v132, v18 offset:80
	v_mul_f32_e32 v18, v19, v144
	v_mul_f32_e32 v22, 0xbfb8aa3b, v18
	v_exp_f32_e32 v22, v22
	v_mul_f32_e32 v19, v23, v144
	v_add_f32_e32 v22, 1.0, v22
	v_rcp_f32_e32 v22, v22
	s_nop 0
	v_mul_f32_e32 v18, v18, v22
	v_mul_f32_e32 v18, v19, v18
	v_cvt_pk_bf16_f32 v18, v18, s0
	ds_write_b16 v132, v18 offset:112
	v_mul_f32_e32 v18, v28, v141
	v_mul_f32_e32 v22, 0xbfb8aa3b, v18
	v_exp_f32_e32 v22, v22
	v_mul_f32_e32 v19, v32, v141
	v_add_f32_e32 v22, 1.0, v22
	v_rcp_f32_e32 v22, v22
	s_nop 0
	v_mul_f32_e32 v18, v18, v22
	v_mul_f32_e32 v18, v19, v18
	v_cvt_pk_bf16_f32 v18, v18, s0
	ds_write_b16 v132, v18 offset:160
	v_mul_f32_e32 v18, v20, v141
	v_mul_f32_e32 v20, 0xbfb8aa3b, v18
	v_exp_f32_e32 v20, v20
	v_mul_f32_e32 v19, v24, v141
	v_add_f32_e32 v20, 1.0, v20
	v_rcp_f32_e32 v20, v20
	s_nop 0
	v_mul_f32_e32 v18, v18, v20
	v_mul_f32_e32 v18, v19, v18
	v_cvt_pk_bf16_f32 v18, v18, s0
	ds_write_b16 v132, v18 offset:192
	v_mul_f32_e32 v18, v29, v139
	v_mul_f32_e32 v20, 0xbfb8aa3b, v18
	v_exp_f32_e32 v20, v20
	v_mul_f32_e32 v19, v33, v139
	v_add_f32_e32 v20, 1.0, v20
	v_rcp_f32_e32 v20, v20
	s_nop 0
	v_mul_f32_e32 v18, v18, v20
	v_mul_f32_e32 v18, v19, v18
	v_cvt_pk_bf16_f32 v18, v18, s0
	ds_write_b16 v132, v18 offset:240
	v_mul_f32_e32 v18, v21, v139
	v_mul_f32_e32 v20, 0xbfb8aa3b, v18
	v_exp_f32_e32 v20, v20
	v_mul_f32_e32 v19, v25, v139
	v_add_f32_e32 v20, 1.0, v20
	v_rcp_f32_e32 v20, v20
	s_nop 0
	v_mul_f32_e32 v18, v18, v20
	v_mul_f32_e32 v18, v19, v18
	v_cvt_pk_bf16_f32 v18, v18, s0
	ds_write_b16 v132, v18 offset:272
	ds_read_b128 v[18:21], v0
	s_mov_b32 s0, 0x87000
	v_add_co_u32_e32 v22, vcc, s0, v130
	s_nop 1
	v_addc_co_u32_e32 v23, vcc, 0, v131, vcc
	s_waitcnt lgkmcnt(0)
	global_store_dwordx4 v[22:23], v[18:21], off
	v_mul_f32_e32 v10, v10, v152
	s_nop 0
	v_mul_f32_e32 v18, 0xbfb8aa3b, v10
	v_exp_f32_e32 v18, v18
	v_mul_f32_e32 v14, v14, v152
	v_mul_f32_e32 v2, v2, v152
	v_mul_f32_e32 v6, v6, v152
	v_add_f32_e32 v18, 1.0, v18
	v_rcp_f32_e32 v18, v18
	s_nop 0
	v_mul_f32_e32 v10, v10, v18
	v_mul_f32_e32 v10, v14, v10
	v_cvt_pk_bf16_f32 v10, v10, s0
	ds_write_b16 v132, v10
	v_mul_f32_e32 v10, 0xbfb8aa3b, v2
	v_exp_f32_e32 v10, v10
	s_nop 0
	v_add_f32_e32 v10, 1.0, v10
	v_rcp_f32_e32 v10, v10
	s_nop 0
	v_mul_f32_e32 v2, v2, v10
	v_mul_f32_e32 v2, v6, v2
	v_cvt_pk_bf16_f32 v2, v2, s0
	ds_write_b16 v132, v2 offset:32
	v_mul_f32_e32 v2, v11, v149
	v_mul_f32_e32 v10, 0xbfb8aa3b, v2
	v_exp_f32_e32 v10, v10
	v_mul_f32_e32 v6, v15, v149
	v_add_f32_e32 v10, 1.0, v10
	v_rcp_f32_e32 v10, v10
	s_nop 0
	v_mul_f32_e32 v2, v2, v10
	v_mul_f32_e32 v2, v6, v2
	v_cvt_pk_bf16_f32 v2, v2, s0
	ds_write_b16 v132, v2 offset:80
	v_mul_f32_e32 v2, v3, v149
	v_mul_f32_e32 v6, 0xbfb8aa3b, v2
	v_exp_f32_e32 v6, v6
	v_mul_f32_e32 v3, v7, v149
	v_add_f32_e32 v6, 1.0, v6
	v_rcp_f32_e32 v6, v6
	s_nop 0
	v_mul_f32_e32 v2, v2, v6
	v_mul_f32_e32 v2, v3, v2
	v_cvt_pk_bf16_f32 v2, v2, s0
	ds_write_b16 v132, v2 offset:112
	v_mul_f32_e32 v2, v12, v136
	v_mul_f32_e32 v6, 0xbfb8aa3b, v2
	v_exp_f32_e32 v6, v6
	v_mul_f32_e32 v3, v16, v136
	v_add_f32_e32 v6, 1.0, v6
	v_rcp_f32_e32 v6, v6
	s_nop 0
	v_mul_f32_e32 v2, v2, v6
	v_mul_f32_e32 v2, v3, v2
	v_cvt_pk_bf16_f32 v2, v2, s0
	ds_write_b16 v132, v2 offset:160
	v_mul_f32_e32 v2, v4, v136
	v_mul_f32_e32 v4, 0xbfb8aa3b, v2
	v_exp_f32_e32 v4, v4
	v_mul_f32_e32 v3, v8, v136
	v_add_f32_e32 v4, 1.0, v4
	v_rcp_f32_e32 v4, v4
	s_nop 0
	v_mul_f32_e32 v2, v2, v4
	v_mul_f32_e32 v2, v3, v2
	v_cvt_pk_bf16_f32 v2, v2, s0
	ds_write_b16 v132, v2 offset:192
	v_mul_f32_e32 v2, v13, v133
	v_mul_f32_e32 v4, 0xbfb8aa3b, v2
	v_exp_f32_e32 v4, v4
	v_mul_f32_e32 v3, v17, v133
	v_add_f32_e32 v4, 1.0, v4
	v_rcp_f32_e32 v4, v4
	s_nop 0
	v_mul_f32_e32 v2, v2, v4
	v_mul_f32_e32 v2, v3, v2
	v_cvt_pk_bf16_f32 v2, v2, s0
	ds_write_b16 v132, v2 offset:240
	v_mul_f32_e32 v2, v5, v133
	v_mul_f32_e32 v4, 0xbfb8aa3b, v2
	v_exp_f32_e32 v4, v4
	v_mul_f32_e32 v3, v9, v133
	v_add_f32_e32 v4, 1.0, v4
	v_rcp_f32_e32 v4, v4
	s_nop 0
	v_mul_f32_e32 v2, v2, v4
	v_mul_f32_e32 v2, v3, v2
	v_cvt_pk_bf16_f32 v2, v2, s0
	ds_write_b16 v132, v2 offset:272
	ds_read_b128 v[2:5], v0
	v_add_co_u32_e32 v6, vcc, 0x9d000, v130
	s_nop 1
	v_addc_co_u32_e32 v7, vcc, 0, v131, vcc
	s_waitcnt lgkmcnt(0)
	global_store_dwordx4 v[6:7], v[2:5], off offset:2048
	s_andn2_b64 vcc, exec, s[6:7]
	s_mov_b64 s[56:57], -1
	s_barrier
	s_cbranch_vccz .LBB0_467

; #define MFMA16(a, b, c) __builtin_amdgcn_mfma_f32_16x16x32_bf16((a), (b), (c), 0, 0, 0)
; template <class Epi>
; DI void gemm8_tile(const bf16_t* __restrict__ Ab, int lda, const bf16_t* __restrict__ Bb, int ldb, int K, int brow, int bcol, const Epi epi,
;                    bool staged, bool has_next, const bf16_t* __restrict__ Abn, const bf16_t* __restrict__ Bbn) {
;     ...
;       for (int m = 0; m < 8; ++m)
; #pragma unroll
;         for (int n = 0; n < 4; ++n) acc[m][n] = MFMA16(At[m], Bf[n], acc[m][n]);
;       __builtin_amdgcn_sched_barrier(0);
;     }
;     asm volatile("s_waitcnt vmcnt(0)" ::: "memory");
;     __syncthreads();
;   DI void run8(f32x4 (&acc)[8][4], int rb, int cb, int fr, int fq) const {
;     const int lane = fq * 16 + fr, wid = (int)(threadIdx.x >> 6);
;     bf16_t* scr = (bf16_t*)(smem + G8_STAGE_B + wid * 1280);
;     const int srow = lane >> 2, sch = lane & 3;
;     bf16_t* ap = act + (size_t)(rb + srow) * LDA + (cb >> 1) + sch * 8;
;     float rsv[8][4];
; #pragma unroll
;     for (int m = 0; m < 8; ++m)
; #pragma unroll
;       for (int j = 0; j < 4; ++j) rsv[m][j] = rsqrtf(ssq[rb + m * 16 + fq * 4 + j] * (1.f / D) + EPS);
.LBB0_1667:
	s_waitcnt lgkmcnt(0)
	v_mfma_f32_16x16x32_bf16 v[122:125], v[58:61], v[2:5], v[126:129]
	v_mfma_f32_16x16x32_bf16 v[126:129], v[58:61], v[138:141], v[146:149]
	v_mfma_f32_16x16x32_bf16 v[114:117], v[58:61], v[142:145], v[118:121]
	v_mfma_f32_16x16x32_bf16 v[118:121], v[58:61], v[202:205], v[150:153]
	v_mfma_f32_16x16x32_bf16 v[106:109], v[50:53], v[2:5], v[110:113]
	v_mfma_f32_16x16x32_bf16 v[110:113], v[50:53], v[138:141], v[154:157]
	v_mfma_f32_16x16x32_bf16 v[98:101], v[50:53], v[142:145], v[102:105]
	v_mfma_f32_16x16x32_bf16 v[102:105], v[50:53], v[202:205], v[158:161]
	v_mfma_f32_16x16x32_bf16 v[90:93], v[42:45], v[2:5], v[94:97]
	v_mfma_f32_16x16x32_bf16 v[94:97], v[42:45], v[138:141], v[162:165]
	v_mfma_f32_16x16x32_bf16 v[82:85], v[42:45], v[142:145], v[86:89]
	v_mfma_f32_16x16x32_bf16 v[86:89], v[42:45], v[202:205], v[166:169]
	v_mfma_f32_16x16x32_bf16 v[74:77], v[34:37], v[2:5], v[78:81]
	v_mfma_f32_16x16x32_bf16 v[78:81], v[34:37], v[138:141], v[170:173]
	v_mfma_f32_16x16x32_bf16 v[66:69], v[34:37], v[142:145], v[70:73]
	v_mfma_f32_16x16x32_bf16 v[70:73], v[34:37], v[202:205], v[174:177]
	v_mfma_f32_16x16x32_bf16 v[58:61], v[26:29], v[2:5], v[62:65]
	v_mfma_f32_16x16x32_bf16 v[62:65], v[26:29], v[138:141], v[178:181]
	v_mfma_f32_16x16x32_bf16 v[50:53], v[26:29], v[142:145], v[54:57]
	v_mfma_f32_16x16x32_bf16 v[54:57], v[26:29], v[202:205], v[182:185]
	v_mfma_f32_16x16x32_bf16 v[42:45], v[18:21], v[2:5], v[46:49]
	v_mfma_f32_16x16x32_bf16 v[46:49], v[18:21], v[138:141], v[186:189]
	v_mfma_f32_16x16x32_bf16 v[34:37], v[18:21], v[142:145], v[38:41]
	v_mfma_f32_16x16x32_bf16 v[38:41], v[18:21], v[202:205], v[190:193]
	v_mfma_f32_16x16x32_bf16 v[26:29], v[10:13], v[2:5], v[30:33]
	v_mfma_f32_16x16x32_bf16 v[30:33], v[10:13], v[138:141], v[194:197]
	v_mfma_f32_16x16x32_bf16 v[18:21], v[10:13], v[142:145], v[22:25]
	v_mfma_f32_16x16x32_bf16 v[22:25], v[10:13], v[202:205], v[198:201]
	v_mfma_f32_16x16x32_bf16 v[10:13], v[206:209], v[2:5], v[14:17]
	v_mfma_f32_16x16x32_bf16 v[14:17], v[206:209], v[138:141], v[130:133]
	v_mfma_f32_16x16x32_bf16 v[2:5], v[206:209], v[142:145], v[6:9]
	v_mfma_f32_16x16x32_bf16 v[6:9], v[206:209], v[202:205], v[134:137]
	v_lshrrev_b32_e32 v168, 4, v228
	v_add_u32_e32 v130, s3, v230
	v_lshl_or_b32 v131, v229, 6, s31
	v_or_b32_e32 v0, v130, v222
	v_lshl_or_b32 v130, v168, 2, v130
	v_ashrrev_i32_e32 v134, 1, v131
	v_ashrrev_i32_e32 v131, 31, v130
	v_lshl_add_u64 v[130:131], v[130:131], 2, s[60:61]
	s_waitcnt vmcnt(0)
	s_waitcnt vmcnt(0)
	s_barrier
	global_load_dwordx4 v[138:141], v[130:131], off
	global_load_dwordx4 v[176:179], v[130:131], off offset:64
	global_load_dwordx4 v[180:183], v[130:131], off offset:128
	global_load_dwordx4 v[184:187], v[130:131], off offset:192
	global_load_dwordx4 v[188:191], v[130:131], off offset:256
	global_load_dwordx4 v[192:195], v[130:131], off offset:320
	global_load_dwordx4 v[170:173], v[130:131], off offset:384
	global_load_dwordx4 v[196:199], v[130:131], off offset:448
	s_mov_b32 s0, 0x358637bd
	v_mov_b64_e32 v[136:137], s[0:1]
	v_ashrrev_i32_e32 v135, 31, v134
	s_waitcnt vmcnt(7)
	v_pk_fma_f32 v[132:133], v[138:139], s[86:87], v[136:137] op_sel_hi:[1,0,0]
	v_rsq_f32_e32 v167, v132
	s_nop 0
	v_mul_f32_e32 v122, v122, v167
	v_mul_f32_e32 v126, v126, v167
	v_mul_f32_e32 v114, v114, v167
	v_rsq_f32_e32 v166, v133
	v_pk_fma_f32 v[132:133], v[140:141], s[86:87], v[136:137] op_sel_hi:[1,0,0]
	v_mul_f32_e32 v118, v118, v167
	v_rsq_f32_e32 v165, v132
	v_rsq_f32_e32 v163, v133
	s_waitcnt vmcnt(6)
	v_pk_fma_f32 v[132:133], v[176:177], s[86:87], v[136:137] op_sel_hi:[1,0,0]
	v_rsq_f32_e32 v164, v132
	v_rsq_f32_e32 v162, v133
	v_pk_fma_f32 v[132:133], v[178:179], s[86:87], v[136:137] op_sel_hi:[1,0,0]
	v_rsq_f32_e32 v161, v132
	v_rsq_f32_e32 v159, v133
	s_waitcnt vmcnt(5)
	v_pk_fma_f32 v[132:133], v[180:181], s[86:87], v[136:137] op_sel_hi:[1,0,0]
	v_rsq_f32_e32 v160, v132
	v_rsq_f32_e32 v158, v133
	v_pk_fma_f32 v[132:133], v[182:183], s[86:87], v[136:137] op_sel_hi:[1,0,0]
	v_rsq_f32_e32 v157, v132
	v_rsq_f32_e32 v155, v133
	s_waitcnt vmcnt(4)
	v_pk_fma_f32 v[132:133], v[184:185], s[86:87], v[136:137] op_sel_hi:[1,0,0]
	v_rsq_f32_e32 v156, v132
	v_rsq_f32_e32 v154, v133
	v_pk_fma_f32 v[132:133], v[186:187], s[86:87], v[136:137] op_sel_hi:[1,0,0]
	v_rsq_f32_e32 v153, v132
	v_rsq_f32_e32 v150, v133
	s_waitcnt vmcnt(3)
	v_pk_fma_f32 v[132:133], v[188:189], s[86:87], v[136:137] op_sel_hi:[1,0,0]
	v_rsq_f32_e32 v151, v132
	v_rsq_f32_e32 v148, v133
	v_pk_fma_f32 v[132:133], v[190:191], s[86:87], v[136:137] op_sel_hi:[1,0,0]
	v_rsq_f32_e32 v146, v132
	v_rsq_f32_e32 v143, v133
	s_waitcnt vmcnt(2)
	v_pk_fma_f32 v[132:133], v[192:193], s[86:87], v[136:137] op_sel_hi:[1,0,0]
	v_rsq_f32_e32 v145, v132
	v_rsq_f32_e32 v142, v133
	v_pk_fma_f32 v[132:133], v[194:195], s[86:87], v[136:137] op_sel_hi:[1,0,0]
	v_rsq_f32_e32 v140, v132
	v_rsq_f32_e32 v138, v133
	s_waitcnt vmcnt(1)
	v_pk_fma_f32 v[132:133], v[170:171], s[86:87], v[136:137] op_sel_hi:[1,0,0]
	v_rsq_f32_e32 v147, v132
	v_rsq_f32_e32 v144, v133
	v_pk_fma_f32 v[132:133], v[172:173], s[86:87], v[136:137] op_sel_hi:[1,0,0]
	v_rsq_f32_e32 v141, v132
	v_rsq_f32_e32 v139, v133
	s_waitcnt vmcnt(0)
; DI bf16_t to_bf16(float x) { return (bf16_t)(pack_bf16(x, 0.f) & 0xffffu); }
;   DI void run8(f32x4 (&acc)[8][4], int rb, int cb, int fr, int fq) const {
;     ...
;       for (int j = 0; j < 4; ++j) rsv[m][j] = rsqrtf(ssq[rb + m * 16 + fq * 4 + j] * (1.f / D) + EPS);
; #pragma unroll
;     for (int m = 0; m < 8; ++m) {
; #pragma unroll
;       for (int j = 0; j < 4; ++j)
; #pragma unroll
;         for (int pi = 0; pi < 2; ++pi) {
;           const float g = acc[m][2 * pi][j] * rsv[m][j], u = acc[m][2 * pi + 1][j] * rsv[m][j];
;           const float a = g * __builtin_amdgcn_rcpf(1.f + __expf(-g)) * u;
;           scr[(fq * 4 + j) * 40 + pi * 16 + fr] = to_bf16(a);
;         }
;       __builtin_amdgcn_sched_barrier(0);
;       const u32x4 o = *(const u32x4*)(scr + srow * 40 + sch * 8);
;       *(u32x4*)(ap + (size_t)(m * 16) * LDA) = o;
;       __builtin_amdgcn_sched_barrier(0);
;     }
	v_pk_fma_f32 v[130:131], v[196:197], s[86:87], v[136:137] op_sel_hi:[1,0,0]
	v_rsq_f32_e32 v152, v130
	v_rsq_f32_e32 v149, v131
	v_pk_fma_f32 v[130:131], v[198:199], s[86:87], v[136:137] op_sel_hi:[1,0,0]
	v_rsq_f32_e32 v136, v130
	s_movk_i32 s0, 0x1680
	v_lshlrev_b32_e32 v132, 1, v223
	v_rsq_f32_e32 v133, v131
	v_mov_b64_e32 v[130:131], s[52:53]
	v_mad_i64_i32 v[130:131], s[0:1], v0, s0, v[130:131]
	v_lshlrev_b32_e32 v0, 4, v223
	v_lshl_add_u64 v[130:131], v[134:135], 1, v[130:131]
	v_and_b32_e32 v0, 48, v0
	v_mul_u32_u24_e32 v134, 0x50, v222
	v_lshl_add_u64 v[130:131], v[130:131], 0, v[0:1]
	v_add3_u32 v0, v217, v134, v0
	v_mul_u32_u24_e32 v134, 0x140, v168
	v_add3_u32 v132, v217, v132, v134
	v_mul_f32_e32 v134, 0xbfb8aa3b, v122
	v_exp_f32_e32 v134, v134
	s_nop 0
	v_add_f32_e32 v134, 1.0, v134
	v_rcp_f32_e32 v134, v134
	s_nop 0
	v_mul_f32_e32 v122, v122, v134
	v_mul_f32_e32 v122, v126, v122
	v_cvt_pk_bf16_f32 v122, v122, s0
	ds_write_b16 v132, v122
	v_mul_f32_e32 v122, 0xbfb8aa3b, v114
	v_exp_f32_e32 v122, v122
	s_nop 0
	v_add_f32_e32 v122, 1.0, v122
	v_rcp_f32_e32 v122, v122
	s_nop 0
	v_mul_f32_e32 v114, v114, v122
	v_mul_f32_e32 v114, v118, v114
	v_cvt_pk_bf16_f32 v114, v114, s0
	ds_write_b16 v132, v114 offset:32
	v_mul_f32_e32 v114, v123, v166
	v_mul_f32_e32 v122, 0xbfb8aa3b, v114
	v_exp_f32_e32 v122, v122
	v_mul_f32_e32 v118, v127, v166
	v_add_f32_e32 v122, 1.0, v122
	v_rcp_f32_e32 v122, v122
	s_nop 0
	v_mul_f32_e32 v114, v114, v122
	v_mul_f32_e32 v114, v118, v114
	v_cvt_pk_bf16_f32 v114, v114, s0
	ds_write_b16 v132, v114 offset:80
	v_mul_f32_e32 v114, v115, v166
	v_mul_f32_e32 v118, 0xbfb8aa3b, v114
	v_exp_f32_e32 v118, v118
	v_mul_f32_e32 v115, v119, v166
	v_add_f32_e32 v118, 1.0, v118
	v_rcp_f32_e32 v118, v118
	s_nop 0
	v_mul_f32_e32 v114, v114, v118
	v_mul_f32_e32 v114, v115, v114
	v_cvt_pk_bf16_f32 v114, v114, s0
	ds_write_b16 v132, v114 offset:112
	v_mul_f32_e32 v114, v124, v165
	v_mul_f32_e32 v118, 0xbfb8aa3b, v114
	v_exp_f32_e32 v118, v118
	v_mul_f32_e32 v115, v128, v165
	v_add_f32_e32 v118, 1.0, v118
	v_rcp_f32_e32 v118, v118
	s_nop 0
	v_mul_f32_e32 v114, v114, v118
	v_mul_f32_e32 v114, v115, v114
	v_cvt_pk_bf16_f32 v114, v114, s0
	ds_write_b16 v132, v114 offset:160
	v_mul_f32_e32 v114, v116, v165
	v_mul_f32_e32 v116, 0xbfb8aa3b, v114
	v_exp_f32_e32 v116, v116
	v_mul_f32_e32 v115, v120, v165
	v_add_f32_e32 v116, 1.0, v116
	v_rcp_f32_e32 v116, v116
	s_nop 0
	v_mul_f32_e32 v114, v114, v116
	v_mul_f32_e32 v114, v115, v114
	v_cvt_pk_bf16_f32 v114, v114, s0
	ds_write_b16 v132, v114 offset:192
	v_mul_f32_e32 v114, v125, v163
	v_mul_f32_e32 v116, 0xbfb8aa3b, v114
	v_exp_f32_e32 v116, v116
	v_mul_f32_e32 v115, v129, v163
	v_add_f32_e32 v116, 1.0, v116
	v_rcp_f32_e32 v116, v116
	s_nop 0
	v_mul_f32_e32 v114, v114, v116
	v_mul_f32_e32 v114, v115, v114
	v_cvt_pk_bf16_f32 v114, v114, s0
	ds_write_b16 v132, v114 offset:240
	v_mul_f32_e32 v114, v117, v163
	v_mul_f32_e32 v116, 0xbfb8aa3b, v114
	v_exp_f32_e32 v116, v116
	v_mul_f32_e32 v115, v121, v163
	v_add_f32_e32 v116, 1.0, v116
	v_rcp_f32_e32 v116, v116
	s_nop 0
	v_mul_f32_e32 v114, v114, v116
	v_mul_f32_e32 v114, v115, v114
	v_cvt_pk_bf16_f32 v114, v114, s0
	ds_write_b16 v132, v114 offset:272
	ds_read_b128 v[114:117], v0
	s_waitcnt lgkmcnt(0)
	global_store_dwordx4 v[130:131], v[114:117], off
	v_mul_f32_e32 v106, v106, v164
	s_nop 0
	v_mul_f32_e32 v114, 0xbfb8aa3b, v106
	v_exp_f32_e32 v114, v114
	v_mul_f32_e32 v110, v110, v164
	v_mul_f32_e32 v98, v98, v164
	v_mul_f32_e32 v102, v102, v164
	v_add_f32_e32 v114, 1.0, v114
	v_rcp_f32_e32 v114, v114
	s_nop 0
	v_mul_f32_e32 v106, v106, v114
	v_mul_f32_e32 v106, v110, v106
	v_cvt_pk_bf16_f32 v106, v106, s0
	ds_write_b16 v132, v106
	v_mul_f32_e32 v106, 0xbfb8aa3b, v98
	v_exp_f32_e32 v106, v106
	s_nop 0
	v_add_f32_e32 v106, 1.0, v106
	v_rcp_f32_e32 v106, v106
	s_nop 0
	v_mul_f32_e32 v98, v98, v106
	v_mul_f32_e32 v98, v102, v98
	v_cvt_pk_bf16_f32 v98, v98, s0
	ds_write_b16 v132, v98 offset:32
	v_mul_f32_e32 v98, v107, v162
	v_mul_f32_e32 v106, 0xbfb8aa3b, v98
	v_exp_f32_e32 v106, v106
	v_mul_f32_e32 v102, v111, v162
	v_add_f32_e32 v106, 1.0, v106
	v_rcp_f32_e32 v106, v106
	s_nop 0
	v_mul_f32_e32 v98, v98, v106
	v_mul_f32_e32 v98, v102, v98
	v_cvt_pk_bf16_f32 v98, v98, s0
	ds_write_b16 v132, v98 offset:80
	v_mul_f32_e32 v98, v99, v162
	v_mul_f32_e32 v102, 0xbfb8aa3b, v98
	v_exp_f32_e32 v102, v102
	v_mul_f32_e32 v99, v103, v162
	v_add_f32_e32 v102, 1.0, v102
	v_rcp_f32_e32 v102, v102
	s_nop 0
	v_mul_f32_e32 v98, v98, v102
	v_mul_f32_e32 v98, v99, v98
	v_cvt_pk_bf16_f32 v98, v98, s0
	ds_write_b16 v132, v98 offset:112
	v_mul_f32_e32 v98, v108, v161
	v_mul_f32_e32 v102, 0xbfb8aa3b, v98
	v_exp_f32_e32 v102, v102
	v_mul_f32_e32 v99, v112, v161
	v_add_f32_e32 v102, 1.0, v102
	v_rcp_f32_e32 v102, v102
	s_nop 0
	v_mul_f32_e32 v98, v98, v102
	v_mul_f32_e32 v98, v99, v98
	v_cvt_pk_bf16_f32 v98, v98, s0
	ds_write_b16 v132, v98 offset:160
	v_mul_f32_e32 v98, v100, v161
	v_mul_f32_e32 v100, 0xbfb8aa3b, v98
	v_exp_f32_e32 v100, v100
	v_mul_f32_e32 v99, v104, v161
	v_add_f32_e32 v100, 1.0, v100
	v_rcp_f32_e32 v100, v100
	s_nop 0
	v_mul_f32_e32 v98, v98, v100
	v_mul_f32_e32 v98, v99, v98
	v_cvt_pk_bf16_f32 v98, v98, s0
	ds_write_b16 v132, v98 offset:192
	v_mul_f32_e32 v98, v109, v159
	v_mul_f32_e32 v100, 0xbfb8aa3b, v98
	v_exp_f32_e32 v100, v100
	v_mul_f32_e32 v99, v113, v159
	v_add_f32_e32 v100, 1.0, v100
	v_rcp_f32_e32 v100, v100
	s_nop 0
	v_mul_f32_e32 v98, v98, v100
	v_mul_f32_e32 v98, v99, v98
	v_cvt_pk_bf16_f32 v98, v98, s0
	ds_write_b16 v132, v98 offset:240
	v_mul_f32_e32 v98, v101, v159
	v_mul_f32_e32 v100, 0xbfb8aa3b, v98
	v_exp_f32_e32 v100, v100
	v_mul_f32_e32 v99, v105, v159
	v_add_f32_e32 v100, 1.0, v100
	v_rcp_f32_e32 v100, v100
	s_nop 0
	v_mul_f32_e32 v98, v98, v100
	v_mul_f32_e32 v98, v99, v98
	v_cvt_pk_bf16_f32 v98, v98, s0
	ds_write_b16 v132, v98 offset:272
	ds_read_b128 v[98:101], v0
	s_mov_b32 s0, 0x16000
	v_add_co_u32_e32 v102, vcc, s0, v130
	s_nop 1
	v_addc_co_u32_e32 v103, vcc, 0, v131, vcc
	s_waitcnt lgkmcnt(0)
; DI bf16_t to_bf16(float x) { return (bf16_t)(pack_bf16(x, 0.f) & 0xffffu); }
;   DI void run8(f32x4 (&acc)[8][4], int rb, int cb, int fr, int fq) const {
;     ...
;     for (int m = 0; m < 8; ++m) {
; #pragma unroll
;       for (int j = 0; j < 4; ++j)
; #pragma unroll
;         for (int pi = 0; pi < 2; ++pi) {
;           const float g = acc[m][2 * pi][j] * rsv[m][j], u = acc[m][2 * pi + 1][j] * rsv[m][j];
;           const float a = g * __builtin_amdgcn_rcpf(1.f + __expf(-g)) * u;
;           scr[(fq * 4 + j) * 40 + pi * 16 + fr] = to_bf16(a);
;         }
;       __builtin_amdgcn_sched_barrier(0);
;       const u32x4 o = *(const u32x4*)(scr + srow * 40 + sch * 8);
;       *(u32x4*)(ap + (size_t)(m * 16) * LDA) = o;
;       __builtin_amdgcn_sched_barrier(0);
;     }
	global_store_dwordx4 v[102:103], v[98:101], off offset:2048
	v_mul_f32_e32 v90, v90, v160
	s_nop 0
	v_mul_f32_e32 v98, 0xbfb8aa3b, v90
	v_exp_f32_e32 v98, v98
	v_mul_f32_e32 v94, v94, v160
	v_mul_f32_e32 v82, v82, v160
	v_mul_f32_e32 v86, v86, v160
	v_add_f32_e32 v98, 1.0, v98
	v_rcp_f32_e32 v98, v98
	s_nop 0
	v_mul_f32_e32 v90, v90, v98
	v_mul_f32_e32 v90, v94, v90
	v_cvt_pk_bf16_f32 v90, v90, s0
	ds_write_b16 v132, v90
	v_mul_f32_e32 v90, 0xbfb8aa3b, v82
	v_exp_f32_e32 v90, v90
	s_nop 0
	v_add_f32_e32 v90, 1.0, v90
	v_rcp_f32_e32 v90, v90
	s_nop 0
	v_mul_f32_e32 v82, v82, v90
	v_mul_f32_e32 v82, v86, v82
	v_cvt_pk_bf16_f32 v82, v82, s0
	ds_write_b16 v132, v82 offset:32
	v_mul_f32_e32 v82, v91, v158
	v_mul_f32_e32 v90, 0xbfb8aa3b, v82
	v_exp_f32_e32 v90, v90
	v_mul_f32_e32 v86, v95, v158
	v_add_f32_e32 v90, 1.0, v90
	v_rcp_f32_e32 v90, v90
	s_nop 0
	v_mul_f32_e32 v82, v82, v90
	v_mul_f32_e32 v82, v86, v82
	v_cvt_pk_bf16_f32 v82, v82, s0
	ds_write_b16 v132, v82 offset:80
	v_mul_f32_e32 v82, v83, v158
	v_mul_f32_e32 v86, 0xbfb8aa3b, v82
	v_exp_f32_e32 v86, v86
	v_mul_f32_e32 v83, v87, v158
	v_add_f32_e32 v86, 1.0, v86
	v_rcp_f32_e32 v86, v86
	s_nop 0
	v_mul_f32_e32 v82, v82, v86
	v_mul_f32_e32 v82, v83, v82
	v_cvt_pk_bf16_f32 v82, v82, s0
	ds_write_b16 v132, v82 offset:112
	v_mul_f32_e32 v82, v92, v157
	v_mul_f32_e32 v86, 0xbfb8aa3b, v82
	v_exp_f32_e32 v86, v86
	v_mul_f32_e32 v83, v96, v157
	v_add_f32_e32 v86, 1.0, v86
	v_rcp_f32_e32 v86, v86
	s_nop 0
	v_mul_f32_e32 v82, v82, v86
	v_mul_f32_e32 v82, v83, v82
	v_cvt_pk_bf16_f32 v82, v82, s0
	ds_write_b16 v132, v82 offset:160
	v_mul_f32_e32 v82, v84, v157
	v_mul_f32_e32 v84, 0xbfb8aa3b, v82
	v_exp_f32_e32 v84, v84
	v_mul_f32_e32 v83, v88, v157
	v_add_f32_e32 v84, 1.0, v84
	v_rcp_f32_e32 v84, v84
	s_nop 0
	v_mul_f32_e32 v82, v82, v84
	v_mul_f32_e32 v82, v83, v82
	v_cvt_pk_bf16_f32 v82, v82, s0
	ds_write_b16 v132, v82 offset:192
	v_mul_f32_e32 v82, v93, v155
	v_mul_f32_e32 v84, 0xbfb8aa3b, v82
	v_exp_f32_e32 v84, v84
	v_mul_f32_e32 v83, v97, v155
	v_add_f32_e32 v84, 1.0, v84
	v_rcp_f32_e32 v84, v84
	s_nop 0
	v_mul_f32_e32 v82, v82, v84
	v_mul_f32_e32 v82, v83, v82
	v_cvt_pk_bf16_f32 v82, v82, s0
	ds_write_b16 v132, v82 offset:240
	v_mul_f32_e32 v82, v85, v155
	v_mul_f32_e32 v84, 0xbfb8aa3b, v82
	v_exp_f32_e32 v84, v84
	v_mul_f32_e32 v83, v89, v155
	v_add_f32_e32 v84, 1.0, v84
	v_rcp_f32_e32 v84, v84
	s_nop 0
	v_mul_f32_e32 v82, v82, v84
	v_mul_f32_e32 v82, v83, v82
	v_cvt_pk_bf16_f32 v82, v82, s0
	ds_write_b16 v132, v82 offset:272
	ds_read_b128 v[82:85], v0
	s_mov_b32 s0, 0x2d000
	v_add_co_u32_e32 v86, vcc, s0, v130
	s_nop 1
	v_addc_co_u32_e32 v87, vcc, 0, v131, vcc
	s_waitcnt lgkmcnt(0)
	global_store_dwordx4 v[86:87], v[82:85], off
	v_mul_f32_e32 v74, v74, v156
	s_nop 0
	v_mul_f32_e32 v82, 0xbfb8aa3b, v74
	v_exp_f32_e32 v82, v82
	v_mul_f32_e32 v78, v78, v156
	v_mul_f32_e32 v66, v66, v156
	v_mul_f32_e32 v70, v70, v156
	v_add_f32_e32 v82, 1.0, v82
	v_rcp_f32_e32 v82, v82
	s_nop 0
	v_mul_f32_e32 v74, v74, v82
	v_mul_f32_e32 v74, v78, v74
	v_cvt_pk_bf16_f32 v74, v74, s0
	ds_write_b16 v132, v74
	v_mul_f32_e32 v74, 0xbfb8aa3b, v66
	v_exp_f32_e32 v74, v74
	s_nop 0
	v_add_f32_e32 v74, 1.0, v74
	v_rcp_f32_e32 v74, v74
	s_nop 0
	v_mul_f32_e32 v66, v66, v74
	v_mul_f32_e32 v66, v70, v66
	v_cvt_pk_bf16_f32 v66, v66, s0
	ds_write_b16 v132, v66 offset:32
	v_mul_f32_e32 v66, v75, v154
	v_mul_f32_e32 v74, 0xbfb8aa3b, v66
	v_exp_f32_e32 v74, v74
	v_mul_f32_e32 v70, v79, v154
	v_add_f32_e32 v74, 1.0, v74
	v_rcp_f32_e32 v74, v74
	s_nop 0
	v_mul_f32_e32 v66, v66, v74
	v_mul_f32_e32 v66, v70, v66
	v_cvt_pk_bf16_f32 v66, v66, s0
	ds_write_b16 v132, v66 offset:80
	v_mul_f32_e32 v66, v67, v154
	v_mul_f32_e32 v70, 0xbfb8aa3b, v66
	v_exp_f32_e32 v70, v70
	v_mul_f32_e32 v67, v71, v154
	v_add_f32_e32 v70, 1.0, v70
	v_rcp_f32_e32 v70, v70
	s_nop 0
	v_mul_f32_e32 v66, v66, v70
	v_mul_f32_e32 v66, v67, v66
	v_cvt_pk_bf16_f32 v66, v66, s0
	ds_write_b16 v132, v66 offset:112
	v_mul_f32_e32 v66, v76, v153
	v_mul_f32_e32 v70, 0xbfb8aa3b, v66
	v_exp_f32_e32 v70, v70
	v_mul_f32_e32 v67, v80, v153
	v_add_f32_e32 v70, 1.0, v70
	v_rcp_f32_e32 v70, v70
	s_nop 0
	v_mul_f32_e32 v66, v66, v70
	v_mul_f32_e32 v66, v67, v66
	v_cvt_pk_bf16_f32 v66, v66, s0
	ds_write_b16 v132, v66 offset:160
	v_mul_f32_e32 v66, v68, v153
	v_mul_f32_e32 v68, 0xbfb8aa3b, v66
	v_exp_f32_e32 v68, v68
	v_mul_f32_e32 v67, v72, v153
	v_add_f32_e32 v68, 1.0, v68
	v_rcp_f32_e32 v68, v68
	s_nop 0
	v_mul_f32_e32 v66, v66, v68
	v_mul_f32_e32 v66, v67, v66
	v_cvt_pk_bf16_f32 v66, v66, s0
	ds_write_b16 v132, v66 offset:192
	v_mul_f32_e32 v66, v77, v150
	v_mul_f32_e32 v68, 0xbfb8aa3b, v66
	v_exp_f32_e32 v68, v68
	v_mul_f32_e32 v67, v81, v150
	v_add_f32_e32 v68, 1.0, v68
	v_rcp_f32_e32 v68, v68
	s_nop 0
	v_mul_f32_e32 v66, v66, v68
	v_mul_f32_e32 v66, v67, v66
	v_cvt_pk_bf16_f32 v66, v66, s0
	ds_write_b16 v132, v66 offset:240
	v_mul_f32_e32 v66, v69, v150
	v_mul_f32_e32 v68, 0xbfb8aa3b, v66
	v_exp_f32_e32 v68, v68
	v_mul_f32_e32 v67, v73, v150
	v_add_f32_e32 v68, 1.0, v68
	v_rcp_f32_e32 v68, v68
	s_nop 0
	v_mul_f32_e32 v66, v66, v68
	v_mul_f32_e32 v66, v67, v66
	v_cvt_pk_bf16_f32 v66, v66, s0
	ds_write_b16 v132, v66 offset:272
	ds_read_b128 v[66:69], v0
	s_mov_b32 s0, 0x43000
	v_add_co_u32_e32 v70, vcc, s0, v130
	s_nop 1
	v_addc_co_u32_e32 v71, vcc, 0, v131, vcc
	s_waitcnt lgkmcnt(0)
; DI bf16_t to_bf16(float x) { return (bf16_t)(pack_bf16(x, 0.f) & 0xffffu); }
;   DI void run8(f32x4 (&acc)[8][4], int rb, int cb, int fr, int fq) const {
;     ...
;     for (int m = 0; m < 8; ++m) {
; #pragma unroll
;       for (int j = 0; j < 4; ++j)
; #pragma unroll
;         for (int pi = 0; pi < 2; ++pi) {
;           const float g = acc[m][2 * pi][j] * rsv[m][j], u = acc[m][2 * pi + 1][j] * rsv[m][j];
;           const float a = g * __builtin_amdgcn_rcpf(1.f + __expf(-g)) * u;
;           scr[(fq * 4 + j) * 40 + pi * 16 + fr] = to_bf16(a);
;         }
;       __builtin_amdgcn_sched_barrier(0);
;       const u32x4 o = *(const u32x4*)(scr + srow * 40 + sch * 8);
;       *(u32x4*)(ap + (size_t)(m * 16) * LDA) = o;
;       __builtin_amdgcn_sched_barrier(0);
;     }
	global_store_dwordx4 v[70:71], v[66:69], off offset:2048
	v_mul_f32_e32 v58, v58, v151
	s_nop 0
	v_mul_f32_e32 v66, 0xbfb8aa3b, v58
	v_exp_f32_e32 v66, v66
	v_mul_f32_e32 v62, v62, v151
	v_mul_f32_e32 v50, v50, v151
	v_mul_f32_e32 v54, v54, v151
	v_add_f32_e32 v66, 1.0, v66
	v_rcp_f32_e32 v66, v66
	s_nop 0
	v_mul_f32_e32 v58, v58, v66
	v_mul_f32_e32 v58, v62, v58
	v_cvt_pk_bf16_f32 v58, v58, s0
	ds_write_b16 v132, v58
	v_mul_f32_e32 v58, 0xbfb8aa3b, v50
	v_exp_f32_e32 v58, v58
	s_nop 0
	v_add_f32_e32 v58, 1.0, v58
	v_rcp_f32_e32 v58, v58
	s_nop 0
	v_mul_f32_e32 v50, v50, v58
	v_mul_f32_e32 v50, v54, v50
	v_cvt_pk_bf16_f32 v50, v50, s0
	ds_write_b16 v132, v50 offset:32
	v_mul_f32_e32 v50, v59, v148
	v_mul_f32_e32 v58, 0xbfb8aa3b, v50
	v_exp_f32_e32 v58, v58
	v_mul_f32_e32 v54, v63, v148
	v_add_f32_e32 v58, 1.0, v58
	v_rcp_f32_e32 v58, v58
	s_nop 0
	v_mul_f32_e32 v50, v50, v58
	v_mul_f32_e32 v50, v54, v50
	v_cvt_pk_bf16_f32 v50, v50, s0
	ds_write_b16 v132, v50 offset:80
	v_mul_f32_e32 v50, v51, v148
	v_mul_f32_e32 v54, 0xbfb8aa3b, v50
	v_exp_f32_e32 v54, v54
	v_mul_f32_e32 v51, v55, v148
	v_add_f32_e32 v54, 1.0, v54
	v_rcp_f32_e32 v54, v54
	s_nop 0
	v_mul_f32_e32 v50, v50, v54
	v_mul_f32_e32 v50, v51, v50
	v_cvt_pk_bf16_f32 v50, v50, s0
	ds_write_b16 v132, v50 offset:112
	v_mul_f32_e32 v50, v60, v146
	v_mul_f32_e32 v54, 0xbfb8aa3b, v50
	v_exp_f32_e32 v54, v54
	v_mul_f32_e32 v51, v64, v146
	v_add_f32_e32 v54, 1.0, v54
	v_rcp_f32_e32 v54, v54
	s_nop 0
	v_mul_f32_e32 v50, v50, v54
	v_mul_f32_e32 v50, v51, v50
	v_cvt_pk_bf16_f32 v50, v50, s0
	ds_write_b16 v132, v50 offset:160
	v_mul_f32_e32 v50, v52, v146
	v_mul_f32_e32 v52, 0xbfb8aa3b, v50
	v_exp_f32_e32 v52, v52
	v_mul_f32_e32 v51, v56, v146
	v_add_f32_e32 v52, 1.0, v52
	v_rcp_f32_e32 v52, v52
	s_nop 0
	v_mul_f32_e32 v50, v50, v52
	v_mul_f32_e32 v50, v51, v50
	v_cvt_pk_bf16_f32 v50, v50, s0
	ds_write_b16 v132, v50 offset:192
	v_mul_f32_e32 v50, v61, v143
	v_mul_f32_e32 v52, 0xbfb8aa3b, v50
	v_exp_f32_e32 v52, v52
	v_mul_f32_e32 v51, v65, v143
	v_add_f32_e32 v52, 1.0, v52
	v_rcp_f32_e32 v52, v52
	s_nop 0
	v_mul_f32_e32 v50, v50, v52
	v_mul_f32_e32 v50, v51, v50
	v_cvt_pk_bf16_f32 v50, v50, s0
	ds_write_b16 v132, v50 offset:240
	v_mul_f32_e32 v50, v53, v143
	v_mul_f32_e32 v52, 0xbfb8aa3b, v50
	v_exp_f32_e32 v52, v52
	v_mul_f32_e32 v51, v57, v143
	v_add_f32_e32 v52, 1.0, v52
	v_rcp_f32_e32 v52, v52
	s_nop 0
	v_mul_f32_e32 v50, v50, v52
	v_mul_f32_e32 v50, v51, v50
	v_cvt_pk_bf16_f32 v50, v50, s0
	ds_write_b16 v132, v50 offset:272
	ds_read_b128 v[50:53], v0
	s_mov_b32 s0, 0x5a000
	v_add_co_u32_e32 v54, vcc, s0, v130
	s_nop 1
	v_addc_co_u32_e32 v55, vcc, 0, v131, vcc
	s_waitcnt lgkmcnt(0)
	global_store_dwordx4 v[54:55], v[50:53], off
	v_mul_f32_e32 v42, v42, v145
	s_nop 0
	v_mul_f32_e32 v50, 0xbfb8aa3b, v42
	v_exp_f32_e32 v50, v50
	v_mul_f32_e32 v46, v46, v145
	v_mul_f32_e32 v34, v34, v145
	v_mul_f32_e32 v38, v38, v145
	v_add_f32_e32 v50, 1.0, v50
	v_rcp_f32_e32 v50, v50
	s_nop 0
	v_mul_f32_e32 v42, v42, v50
	v_mul_f32_e32 v42, v46, v42
	v_cvt_pk_bf16_f32 v42, v42, s0
	ds_write_b16 v132, v42
	v_mul_f32_e32 v42, 0xbfb8aa3b, v34
	v_exp_f32_e32 v42, v42
	s_nop 0
	v_add_f32_e32 v42, 1.0, v42
	v_rcp_f32_e32 v42, v42
	s_nop 0
	v_mul_f32_e32 v34, v34, v42
	v_mul_f32_e32 v34, v38, v34
	v_cvt_pk_bf16_f32 v34, v34, s0
	ds_write_b16 v132, v34 offset:32
	v_mul_f32_e32 v34, v43, v142
	v_mul_f32_e32 v42, 0xbfb8aa3b, v34
	v_exp_f32_e32 v42, v42
	v_mul_f32_e32 v38, v47, v142
	v_add_f32_e32 v42, 1.0, v42
	v_rcp_f32_e32 v42, v42
	s_nop 0
	v_mul_f32_e32 v34, v34, v42
	v_mul_f32_e32 v34, v38, v34
	v_cvt_pk_bf16_f32 v34, v34, s0
	ds_write_b16 v132, v34 offset:80
	v_mul_f32_e32 v34, v35, v142
	v_mul_f32_e32 v38, 0xbfb8aa3b, v34
	v_exp_f32_e32 v38, v38
	v_mul_f32_e32 v35, v39, v142
	v_add_f32_e32 v38, 1.0, v38
	v_rcp_f32_e32 v38, v38
	s_nop 0
	v_mul_f32_e32 v34, v34, v38
	v_mul_f32_e32 v34, v35, v34
	v_cvt_pk_bf16_f32 v34, v34, s0
	ds_write_b16 v132, v34 offset:112
	v_mul_f32_e32 v34, v44, v140
	v_mul_f32_e32 v38, 0xbfb8aa3b, v34
	v_exp_f32_e32 v38, v38
	v_mul_f32_e32 v35, v48, v140
	v_add_f32_e32 v38, 1.0, v38
	v_rcp_f32_e32 v38, v38
	s_nop 0
	v_mul_f32_e32 v34, v34, v38
	v_mul_f32_e32 v34, v35, v34
	v_cvt_pk_bf16_f32 v34, v34, s0
	ds_write_b16 v132, v34 offset:160
	v_mul_f32_e32 v34, v36, v140
	v_mul_f32_e32 v36, 0xbfb8aa3b, v34
	v_exp_f32_e32 v36, v36
	v_mul_f32_e32 v35, v40, v140
	v_add_f32_e32 v36, 1.0, v36
	v_rcp_f32_e32 v36, v36
	s_nop 0
	v_mul_f32_e32 v34, v34, v36
	v_mul_f32_e32 v34, v35, v34
	v_cvt_pk_bf16_f32 v34, v34, s0
	ds_write_b16 v132, v34 offset:192
	v_mul_f32_e32 v34, v45, v138
	v_mul_f32_e32 v36, 0xbfb8aa3b, v34
	v_exp_f32_e32 v36, v36
	v_mul_f32_e32 v35, v49, v138
	v_add_f32_e32 v36, 1.0, v36
	v_rcp_f32_e32 v36, v36
	s_nop 0
	v_mul_f32_e32 v34, v34, v36
	v_mul_f32_e32 v34, v35, v34
	v_cvt_pk_bf16_f32 v34, v34, s0
	ds_write_b16 v132, v34 offset:240
	v_mul_f32_e32 v34, v37, v138
	v_mul_f32_e32 v36, 0xbfb8aa3b, v34
	v_exp_f32_e32 v36, v36
	v_mul_f32_e32 v35, v41, v138
	v_add_f32_e32 v36, 1.0, v36
	v_rcp_f32_e32 v36, v36
	s_nop 0
	v_mul_f32_e32 v34, v34, v36
	v_mul_f32_e32 v34, v35, v34
	v_cvt_pk_bf16_f32 v34, v34, s0
	ds_write_b16 v132, v34 offset:272
	ds_read_b128 v[34:37], v0
	v_add_co_u32_e32 v38, vcc, s68, v130
	s_nop 1
	v_addc_co_u32_e32 v39, vcc, 0, v131, vcc
	s_waitcnt lgkmcnt(0)
; DI bf16_t to_bf16(float x) { return (bf16_t)(pack_bf16(x, 0.f) & 0xffffu); }
; template <class Epi>
; DI void gemm8_tile(const bf16_t* __restrict__ Ab, int lda, const bf16_t* __restrict__ Bb, int ldb, int K, int brow, int bcol, const Epi epi,
;                    bool staged, bool has_next, const bf16_t* __restrict__ Abn, const bf16_t* __restrict__ Bbn) {
;     ...
;   if (Epi::LDS_SCRATCH) __syncthreads();
;   DI void run8(f32x4 (&acc)[8][4], int rb, int cb, int fr, int fq) const {
;     ...
;     for (int m = 0; m < 8; ++m) {
; #pragma unroll
;       for (int j = 0; j < 4; ++j)
; #pragma unroll
;         for (int pi = 0; pi < 2; ++pi) {
;           const float g = acc[m][2 * pi][j] * rsv[m][j], u = acc[m][2 * pi + 1][j] * rsv[m][j];
;           const float a = g * __builtin_amdgcn_rcpf(1.f + __expf(-g)) * u;
;           scr[(fq * 4 + j) * 40 + pi * 16 + fr] = to_bf16(a);
;         }
;       __builtin_amdgcn_sched_barrier(0);
;       const u32x4 o = *(const u32x4*)(scr + srow * 40 + sch * 8);
;       *(u32x4*)(ap + (size_t)(m * 16) * LDA) = o;
;       __builtin_amdgcn_sched_barrier(0);
;     }
	global_store_dwordx4 v[38:39], v[34:37], off offset:2048
	v_mul_f32_e32 v26, v26, v147
	s_nop 0
	v_mul_f32_e32 v34, 0xbfb8aa3b, v26
	v_exp_f32_e32 v34, v34
	v_mul_f32_e32 v30, v30, v147
	v_mul_f32_e32 v18, v18, v147
	v_mul_f32_e32 v22, v22, v147
	v_add_f32_e32 v34, 1.0, v34
	v_rcp_f32_e32 v34, v34
	s_nop 0
	v_mul_f32_e32 v26, v26, v34
	v_mul_f32_e32 v26, v30, v26
	v_cvt_pk_bf16_f32 v26, v26, s0
	ds_write_b16 v132, v26
	v_mul_f32_e32 v26, 0xbfb8aa3b, v18
	v_exp_f32_e32 v26, v26
	s_nop 0
	v_add_f32_e32 v26, 1.0, v26
	v_rcp_f32_e32 v26, v26
	s_nop 0
	v_mul_f32_e32 v18, v18, v26
	v_mul_f32_e32 v18, v22, v18
	v_cvt_pk_bf16_f32 v18, v18, s0
	ds_write_b16 v132, v18 offset:32
	v_mul_f32_e32 v18, v27, v144
	v_mul_f32_e32 v26, 0xbfb8aa3b, v18
	v_exp_f32_e32 v26, v26
	v_mul_f32_e32 v22, v31, v144
	v_add_f32_e32 v26, 1.0, v26
	v_rcp_f32_e32 v26, v26
	s_nop 0
	v_mul_f32_e32 v18, v18, v26
	v_mul_f32_e32 v18, v22, v18
	v_cvt_pk_bf16_f32 v18, v18, s0
	ds_write_b16 v132, v18 offset:80
	v_mul_f32_e32 v18, v19, v144
	v_mul_f32_e32 v22, 0xbfb8aa3b, v18
	v_exp_f32_e32 v22, v22
	v_mul_f32_e32 v19, v23, v144
	v_add_f32_e32 v22, 1.0, v22
	v_rcp_f32_e32 v22, v22
	s_nop 0
	v_mul_f32_e32 v18, v18, v22
	v_mul_f32_e32 v18, v19, v18
	v_cvt_pk_bf16_f32 v18, v18, s0
	ds_write_b16 v132, v18 offset:112
	v_mul_f32_e32 v18, v28, v141
	v_mul_f32_e32 v22, 0xbfb8aa3b, v18
	v_exp_f32_e32 v22, v22
	v_mul_f32_e32 v19, v32, v141
	v_add_f32_e32 v22, 1.0, v22
	v_rcp_f32_e32 v22, v22
	s_nop 0
	v_mul_f32_e32 v18, v18, v22
	v_mul_f32_e32 v18, v19, v18
	v_cvt_pk_bf16_f32 v18, v18, s0
	ds_write_b16 v132, v18 offset:160
	v_mul_f32_e32 v18, v20, v141
	v_mul_f32_e32 v20, 0xbfb8aa3b, v18
	v_exp_f32_e32 v20, v20
	v_mul_f32_e32 v19, v24, v141
	v_add_f32_e32 v20, 1.0, v20
	v_rcp_f32_e32 v20, v20
	s_nop 0
	v_mul_f32_e32 v18, v18, v20
	v_mul_f32_e32 v18, v19, v18
	v_cvt_pk_bf16_f32 v18, v18, s0
	ds_write_b16 v132, v18 offset:192
	v_mul_f32_e32 v18, v29, v139
	v_mul_f32_e32 v20, 0xbfb8aa3b, v18
	v_exp_f32_e32 v20, v20
	v_mul_f32_e32 v19, v33, v139
	v_add_f32_e32 v20, 1.0, v20
	v_rcp_f32_e32 v20, v20
	s_nop 0
	v_mul_f32_e32 v18, v18, v20
	v_mul_f32_e32 v18, v19, v18
	v_cvt_pk_bf16_f32 v18, v18, s0
	ds_write_b16 v132, v18 offset:240
	v_mul_f32_e32 v18, v21, v139
	v_mul_f32_e32 v20, 0xbfb8aa3b, v18
	v_exp_f32_e32 v20, v20
	v_mul_f32_e32 v19, v25, v139
	v_add_f32_e32 v20, 1.0, v20
	v_rcp_f32_e32 v20, v20
	s_nop 0
	v_mul_f32_e32 v18, v18, v20
	v_mul_f32_e32 v18, v19, v18
	v_cvt_pk_bf16_f32 v18, v18, s0
	ds_write_b16 v132, v18 offset:272
	ds_read_b128 v[18:21], v0
	s_mov_b32 s0, 0x87000
	v_add_co_u32_e32 v22, vcc, s0, v130
	s_nop 1
	v_addc_co_u32_e32 v23, vcc, 0, v131, vcc
	s_waitcnt lgkmcnt(0)
	global_store_dwordx4 v[22:23], v[18:21], off
	v_mul_f32_e32 v10, v10, v152
	s_nop 0
	v_mul_f32_e32 v18, 0xbfb8aa3b, v10
	v_exp_f32_e32 v18, v18
	v_mul_f32_e32 v14, v14, v152
	v_mul_f32_e32 v2, v2, v152
	v_mul_f32_e32 v6, v6, v152
	v_add_f32_e32 v18, 1.0, v18
	v_rcp_f32_e32 v18, v18
	s_nop 0
	v_mul_f32_e32 v10, v10, v18
	v_mul_f32_e32 v10, v14, v10
	v_cvt_pk_bf16_f32 v10, v10, s0
	ds_write_b16 v132, v10
	v_mul_f32_e32 v10, 0xbfb8aa3b, v2
	v_exp_f32_e32 v10, v10
	s_nop 0
	v_add_f32_e32 v10, 1.0, v10
	v_rcp_f32_e32 v10, v10
	s_nop 0
	v_mul_f32_e32 v2, v2, v10
	v_mul_f32_e32 v2, v6, v2
	v_cvt_pk_bf16_f32 v2, v2, s0
	ds_write_b16 v132, v2 offset:32
	v_mul_f32_e32 v2, v11, v149
	v_mul_f32_e32 v10, 0xbfb8aa3b, v2
	v_exp_f32_e32 v10, v10
	v_mul_f32_e32 v6, v15, v149
	v_add_f32_e32 v10, 1.0, v10
	v_rcp_f32_e32 v10, v10
	s_nop 0
	v_mul_f32_e32 v2, v2, v10
	v_mul_f32_e32 v2, v6, v2
	v_cvt_pk_bf16_f32 v2, v2, s0
	ds_write_b16 v132, v2 offset:80
	v_mul_f32_e32 v2, v3, v149
	v_mul_f32_e32 v6, 0xbfb8aa3b, v2
	v_exp_f32_e32 v6, v6
	v_mul_f32_e32 v3, v7, v149
	v_add_f32_e32 v6, 1.0, v6
	v_rcp_f32_e32 v6, v6
	s_nop 0
	v_mul_f32_e32 v2, v2, v6
	v_mul_f32_e32 v2, v3, v2
	v_cvt_pk_bf16_f32 v2, v2, s0
	ds_write_b16 v132, v2 offset:112
	v_mul_f32_e32 v2, v12, v136
	v_mul_f32_e32 v6, 0xbfb8aa3b, v2
	v_exp_f32_e32 v6, v6
	v_mul_f32_e32 v3, v16, v136
	v_add_f32_e32 v6, 1.0, v6
	v_rcp_f32_e32 v6, v6
	s_nop 0
	v_mul_f32_e32 v2, v2, v6
	v_mul_f32_e32 v2, v3, v2
	v_cvt_pk_bf16_f32 v2, v2, s0
	ds_write_b16 v132, v2 offset:160
	v_mul_f32_e32 v2, v4, v136
	v_mul_f32_e32 v4, 0xbfb8aa3b, v2
	v_exp_f32_e32 v4, v4
	v_mul_f32_e32 v3, v8, v136
	v_add_f32_e32 v4, 1.0, v4
	v_rcp_f32_e32 v4, v4
	s_nop 0
	v_mul_f32_e32 v2, v2, v4
	v_mul_f32_e32 v2, v3, v2
	v_cvt_pk_bf16_f32 v2, v2, s0
	ds_write_b16 v132, v2 offset:192
	v_mul_f32_e32 v2, v13, v133
	v_mul_f32_e32 v4, 0xbfb8aa3b, v2
	v_exp_f32_e32 v4, v4
	v_mul_f32_e32 v3, v17, v133
	v_add_f32_e32 v4, 1.0, v4
	v_rcp_f32_e32 v4, v4
	s_nop 0
	v_mul_f32_e32 v2, v2, v4
	v_mul_f32_e32 v2, v3, v2
	v_cvt_pk_bf16_f32 v2, v2, s0
	ds_write_b16 v132, v2 offset:240
	v_mul_f32_e32 v2, v5, v133
	v_mul_f32_e32 v4, 0xbfb8aa3b, v2
	v_exp_f32_e32 v4, v4
	v_mul_f32_e32 v3, v9, v133
	v_add_f32_e32 v4, 1.0, v4
	v_rcp_f32_e32 v4, v4
	s_nop 0
	v_mul_f32_e32 v2, v2, v4
	v_mul_f32_e32 v2, v3, v2
	v_cvt_pk_bf16_f32 v2, v2, s0
	ds_write_b16 v132, v2 offset:272
	ds_read_b128 v[2:5], v0
	v_add_co_u32_e32 v6, vcc, 0x9d000, v130
	s_nop 1
	v_addc_co_u32_e32 v7, vcc, 0, v131, vcc
	s_waitcnt lgkmcnt(0)
	global_store_dwordx4 v[6:7], v[2:5], off offset:2048
	s_andn2_b64 vcc, exec, s[6:7]
	s_mov_b64 s[0:1], -1
	s_barrier
	s_cbranch_vccz .LBB0_1678
